# transpose phases 4 and 9 fused into the out-projection GEMMs: A operand read channel-major via ds_read_b64_tr_b16 with LDS-DMA staging
# speedup vs baseline: 1.1239x; 1.0399x over previous
.LBB0_20:
	s_cmp_eq_u32 s2, 4
	s_cbranch_scc1 .LBB0_19
	s_cmp_eq_u32 s2, 9
	s_cbranch_scc1 .LBB0_19
	s_cmp_lt_i32 s2, s82
	s_cselect_b64 s[0:1], -1, 0
	s_cmp_ge_i32 s2, s83
	s_cselect_b64 s[22:23], -1, 0
	s_or_b64 s[0:1], s[0:1], s[22:23]
	s_and_b64 vcc, exec, s[0:1]
	s_cbranch_vccnz .LBB0_19
	s_cmp_le_i32 s2, s82
	v_writelane_b32 v244, s2, 10
	s_cbranch_scc1 .LBB0_75
	s_waitcnt vmcnt(0)
	s_barrier
	s_mov_b64 s[0:1], exec
	v_readlane_b32 s22, v248, 4
	v_readlane_b32 s23, v248, 5
	s_and_b64 s[22:23], s[0:1], s[22:23]
	s_mov_b64 exec, s[22:23]
	s_cbranch_execz .LBB0_74
	s_waitcnt vmcnt(0) expcnt(0) lgkmcnt(0)
	ds_read_b32 v3, v0 offset:49152
	ds_read_b32 v1, v0 offset:49156
	s_waitcnt lgkmcnt(1)
	v_cmp_ne_u32_e32 vcc, 0, v3
	s_cbranch_vccnz .LBB0_38
	v_readlane_b32 s4, v248, 38
	v_readlane_b32 s5, v248, 39
	s_load_dwordx2 s[22:23], s[4:5], 0x4
	s_mov_b32 s24, 1
	s_waitcnt lgkmcnt(0)
	s_mul_i32 s2, s22, s94
	s_mul_i32 s2, s2, s23
	s_branch .LBB0_26

.LBB0_89:
	s_ashr_i32 s0, s2, 31
	s_lshr_b32 s0, s0, 26
	s_add_i32 s0, s2, s0
	s_andn2_b32 s0, s0, 63
	s_sub_i32 s1, s2, s0
	s_bfe_i32 s22, s1, 0x80000
	s_bfe_u32 s22, s22, 0x3000c
	s_add_i32 s23, s1, s22
	s_bfe_i32 s22, s23, 0x80000
	s_sext_i32_i16 s22, s22
	s_and_b32 s22, s22, -8
	s_add_i32 s22, s22, s0
	v_readlane_b32 s0, v246, 0
	s_or_b32 s22, s22, s0
	s_and_b32 s0, s23, 0xf8
	s_sub_i32 s0, s1, s0
	s_sext_i32_i8 s0, s0
	s_lshl_b32 s24, s22, 7
	s_lshl_b32 s23, s0, 7
	s_barrier
	v_lshrrev_b32_e32 v122, 6, v184
	v_and_b32_e32 v123, 63, v184
	v_readfirstlane_b32 s39, v122
	v_lshrrev_b32_e32 v124, 4, v123
	v_and_b32_e32 v125, 15, v123
	v_lshlrev_b32_e32 v126, 2, v124
	v_xor_b32_e32 v125, v125, v126
	v_mul_u32_u24_e32 v124, 0x14000, v124
	v_readlane_b32 s0, v247, 58
	v_readlane_b32 s1, v247, 59
	s_nop 3
	s_lshl_b32 s38, s39, 12
	s_mul_i32 s100, s39, 0x140000
	s_lshl_b32 s28, s24, 1
	s_add_u32 s100, s100, s28
	s_add_u32 s100, s100, 0x604a000
	s_add_u32 s28, s68, s100
	s_addc_u32 s29, s69, 0
	v_xor_b32_e32 v126, 0, v125
	v_lshl_add_u32 v126, v126, 4, v124
	v_mov_b32_e32 v127, 0
	v_lshl_add_u64 v[98:99], v[126:127], 0, s[28:29]
	s_add_u32 s28, s28, 0x50000
	s_addc_u32 s29, s29, 0
	v_xor_b32_e32 v126, 1, v125
	v_lshl_add_u32 v126, v126, 4, v124
	v_mov_b32_e32 v127, 0
	v_lshl_add_u64 v[100:101], v[126:127], 0, s[28:29]
	s_add_u32 s28, s28, 0x50000
	s_addc_u32 s29, s29, 0
	v_xor_b32_e32 v126, 2, v125
	v_lshl_add_u32 v126, v126, 4, v124
	v_mov_b32_e32 v127, 0
	v_lshl_add_u64 v[102:103], v[126:127], 0, s[28:29]
	s_add_u32 s28, s28, 0x50000
	s_addc_u32 s29, s29, 0
	v_xor_b32_e32 v126, 3, v125
	v_lshl_add_u32 v126, v126, 4, v124
	v_mov_b32_e32 v127, 0
	v_lshl_add_u64 v[104:105], v[126:127], 0, s[28:29]
	v_lshrrev_b32_e32 v124, 3, v123
	v_lshrrev_b32_e32 v125, 4, v123
	v_and_b32_e32 v126, 7, v123
	s_lshl_b32 s100, s39, 5
	s_add_i32 s100, s100, s23
	s_lshl_b32 s100, s100, 11
	s_add_u32 s0, s0, s100
	s_addc_u32 s1, s1, 0
	v_and_b32_e32 v127, 7, v125
	v_xor_b32_e32 v127, v126, v127
	v_lshlrev_b32_e32 v127, 4, v127
	v_lshl_add_u32 v128, v124, 11, v127
	v_mov_b32_e32 v96, v128
	v_mov_b32_e32 v97, 0
	v_lshl_add_u64 v[106:107], v[96:97], 0, s[0:1]
	s_add_u32 s0, s0, 0x4000
	s_addc_u32 s1, s1, 0
	v_add_u32_e32 v127, 4, v125
	v_and_b32_e32 v127, 7, v127
	v_xor_b32_e32 v127, v126, v127
	v_lshlrev_b32_e32 v127, 4, v127
	v_lshl_add_u32 v128, v124, 11, v127
	v_mov_b32_e32 v96, v128
	v_mov_b32_e32 v97, 0
	v_lshl_add_u64 v[108:109], v[96:97], 0, s[0:1]
	s_add_u32 s0, s0, 0x4000
	s_addc_u32 s1, s1, 0
	v_and_b32_e32 v127, 7, v125
	v_xor_b32_e32 v127, v126, v127
	v_lshlrev_b32_e32 v127, 4, v127
	v_lshl_add_u32 v128, v124, 11, v127
	v_mov_b32_e32 v96, v128
	v_mov_b32_e32 v97, 0
	v_lshl_add_u64 v[110:111], v[96:97], 0, s[0:1]
	s_add_u32 s0, s0, 0x4000
	s_addc_u32 s1, s1, 0
	v_add_u32_e32 v127, 4, v125
	v_and_b32_e32 v127, 7, v127
	v_xor_b32_e32 v127, v126, v127
	v_lshlrev_b32_e32 v127, 4, v127
	v_lshl_add_u32 v128, v124, 11, v127
	v_mov_b32_e32 v96, v128
	v_mov_b32_e32 v97, 0
	v_lshl_add_u64 v[112:113], v[96:97], 0, s[0:1]
	s_mov_b32 s28, 0x500000
	s_mov_b32 s29, 0
	s_mov_b32 s36, 128
	s_mov_b32 s37, 0
	s_add_u32 m0, s38, 0x0
	s_nop 0
	global_load_lds_dwordx4 v[98:99], off
	v_lshl_add_u64 v[98:99], v[98:99], 0, s[28:29]
	s_add_u32 m0, s38, 0x400
	s_nop 0
	global_load_lds_dwordx4 v[100:101], off
	v_lshl_add_u64 v[100:101], v[100:101], 0, s[28:29]
	s_add_u32 m0, s38, 0x800
	s_nop 0
	global_load_lds_dwordx4 v[102:103], off
	v_lshl_add_u64 v[102:103], v[102:103], 0, s[28:29]
	s_add_u32 m0, s38, 0xc00
	s_nop 0
	global_load_lds_dwordx4 v[104:105], off
	v_lshl_add_u64 v[104:105], v[104:105], 0, s[28:29]
	s_add_u32 m0, s38, 0x4000
	s_nop 0
	global_load_lds_dwordx4 v[106:107], off
	v_lshl_add_u64 v[106:107], v[106:107], 0, s[36:37]
	s_add_u32 m0, s38, 0x4400
	s_nop 0
	global_load_lds_dwordx4 v[108:109], off
	v_lshl_add_u64 v[108:109], v[108:109], 0, s[36:37]
	s_add_u32 m0, s38, 0x4800
	s_nop 0
	global_load_lds_dwordx4 v[110:111], off
	v_lshl_add_u64 v[110:111], v[110:111], 0, s[36:37]
	s_add_u32 m0, s38, 0x4c00
	s_nop 0
	global_load_lds_dwordx4 v[112:113], off
	v_lshl_add_u64 v[112:113], v[112:113], 0, s[36:37]
	v_and_b32_e32 v122, 31, v123
	v_lshrrev_b32_e32 v124, 5, v123
	v_bfe_u32 v125, v123, 4, 1
	v_bfe_u32 v126, v123, 2, 2
	v_and_b32_e32 v127, 3, v123
	s_lshr_b32 s101, s39, 1
	s_and_b32 s39, s39, 1
	v_lshlrev_b32_e32 v96, 1, v124
	v_add_u32_e32 v96, 0, v96
	v_and_b32_e32 v96, 3, v96
	v_lshl_or_b32 v96, v126, 2, v96
	v_lshrrev_b32_e32 v97, 1, v127
	v_lshl_or_b32 v97, v125, 1, v97
	v_or_b32_e32 v97, 0, v97
	s_lshl_b32 s0, s101, 3
	v_or_b32_e32 v97, s0, v97
	v_xor_b32_e32 v97, v97, v96
	v_lshlrev_b32_e32 v96, 3, v124
	v_add3_u32 v96, v96, v126, 0
	v_lshlrev_b32_e32 v96, 8, v96
	v_lshl_add_u32 v96, v97, 4, v96
	v_and_b32_e32 v97, 1, v127
	v_lshl_add_u32 v114, v97, 3, v96
	v_lshlrev_b32_e32 v96, 1, v124
	v_add_u32_e32 v96, 1, v96
	v_and_b32_e32 v96, 3, v96
	v_lshl_or_b32 v96, v126, 2, v96
	v_lshrrev_b32_e32 v97, 1, v127
	v_lshl_or_b32 v97, v125, 1, v97
	v_or_b32_e32 v97, 0, v97
	s_lshl_b32 s0, s101, 3
	v_or_b32_e32 v97, s0, v97
	v_xor_b32_e32 v97, v97, v96
	v_lshlrev_b32_e32 v96, 3, v124
	v_add3_u32 v96, v96, v126, 4
	v_lshlrev_b32_e32 v96, 8, v96
	v_lshl_add_u32 v96, v97, 4, v96
	v_and_b32_e32 v97, 1, v127
	v_lshl_add_u32 v115, v97, 3, v96
	v_lshlrev_b32_e32 v96, 1, v124
	v_add_u32_e32 v96, 0, v96
	v_and_b32_e32 v96, 3, v96
	v_lshl_or_b32 v96, v126, 2, v96
	v_lshrrev_b32_e32 v97, 1, v127
	v_lshl_or_b32 v97, v125, 1, v97
	v_or_b32_e32 v97, 4, v97
	s_lshl_b32 s0, s101, 3
	v_or_b32_e32 v97, s0, v97
	v_xor_b32_e32 v97, v97, v96
	v_lshlrev_b32_e32 v96, 3, v124
	v_add3_u32 v96, v96, v126, 0
	v_lshlrev_b32_e32 v96, 8, v96
	v_lshl_add_u32 v96, v97, 4, v96
	v_and_b32_e32 v97, 1, v127
	v_lshl_add_u32 v116, v97, 3, v96
	v_lshlrev_b32_e32 v96, 1, v124
	v_add_u32_e32 v96, 1, v96
	v_and_b32_e32 v96, 3, v96
	v_lshl_or_b32 v96, v126, 2, v96
	v_lshrrev_b32_e32 v97, 1, v127
	v_lshl_or_b32 v97, v125, 1, v97
	v_or_b32_e32 v97, 4, v97
	s_lshl_b32 s0, s101, 3
	v_or_b32_e32 v97, s0, v97
	v_xor_b32_e32 v97, v97, v96
	v_lshlrev_b32_e32 v96, 3, v124
	v_add3_u32 v96, v96, v126, 4
	v_lshlrev_b32_e32 v96, 8, v96
	v_lshl_add_u32 v96, v97, 4, v96
	v_and_b32_e32 v97, 1, v127
	v_lshl_add_u32 v117, v97, 3, v96
	v_bfe_u32 v96, v122, 1, 3
	v_xor_b32_e32 v96, v96, v124
	v_lshlrev_b32_e32 v96, 4, v96
	v_lshl_add_u32 v96, v122, 7, v96
	s_lshl_b32 s0, s39, 13
	v_add_u32_e32 v118, s0, v96
	v_xor_b32_e32 v119, 0x20, v118
	v_xor_b32_e32 v120, 0x40, v118
	v_xor_b32_e32 v121, 0x60, v118
	v_mov_b32_e32 v2, 0
	v_mov_b32_e32 v3, v2
	v_mov_b32_e32 v4, v2
	v_mov_b32_e32 v5, v2
	v_mov_b32_e32 v6, v2
	v_mov_b32_e32 v7, v2
	v_mov_b32_e32 v8, v2
	v_mov_b32_e32 v9, v2
	v_mov_b32_e32 v10, v2
	v_mov_b32_e32 v11, v2
	v_mov_b32_e32 v12, v2
	v_mov_b32_e32 v13, v2
	v_mov_b32_e32 v14, v2
	v_mov_b32_e32 v15, v2
	v_mov_b32_e32 v16, v2
	v_mov_b32_e32 v17, v2
	v_mov_b32_e32 v18, v2
	v_mov_b32_e32 v19, v2
	v_mov_b32_e32 v20, v2
	v_mov_b32_e32 v21, v2
	v_mov_b32_e32 v22, v2
	v_mov_b32_e32 v23, v2
	v_mov_b32_e32 v24, v2
	v_mov_b32_e32 v25, v2
	v_mov_b32_e32 v26, v2
	v_mov_b32_e32 v27, v2
	v_mov_b32_e32 v28, v2
	v_mov_b32_e32 v29, v2
	v_mov_b32_e32 v30, v2
	v_mov_b32_e32 v31, v2
	v_mov_b32_e32 v32, v2
	v_mov_b32_e32 v33, v2
	v_mov_b32_e32 v34, v2
	v_mov_b32_e32 v35, v2
	v_mov_b32_e32 v36, v2
	v_mov_b32_e32 v37, v2
	v_mov_b32_e32 v38, v2
	v_mov_b32_e32 v39, v2
	v_mov_b32_e32 v40, v2
	v_mov_b32_e32 v41, v2
	v_mov_b32_e32 v42, v2
	v_mov_b32_e32 v43, v2
	v_mov_b32_e32 v44, v2
	v_mov_b32_e32 v45, v2
	v_mov_b32_e32 v46, v2
	v_mov_b32_e32 v47, v2
	v_mov_b32_e32 v48, v2
	v_mov_b32_e32 v49, v2
	v_mov_b32_e32 v50, v2
	v_mov_b32_e32 v51, v2
	v_mov_b32_e32 v52, v2
	v_mov_b32_e32 v53, v2
	v_mov_b32_e32 v54, v2
	v_mov_b32_e32 v55, v2
	v_mov_b32_e32 v56, v2
	v_mov_b32_e32 v57, v2
	v_mov_b32_e32 v58, v2
	v_mov_b32_e32 v59, v2
	v_mov_b32_e32 v60, v2
	v_mov_b32_e32 v61, v2
	v_mov_b32_e32 v62, v2
	v_mov_b32_e32 v63, v2
	v_mov_b32_e32 v64, v2
	v_mov_b32_e32 v65, v2
	s_mov_b32 s100, 7
.LgemmT_p10_loop:
	s_waitcnt vmcnt(0)
	s_barrier
	ds_read_b64_tr_b16 v[66:67], v114 offset:0
	ds_read_b64_tr_b16 v[68:69], v115 offset:0
	ds_read_b64_tr_b16 v[70:71], v116 offset:0
	ds_read_b64_tr_b16 v[72:73], v117 offset:0
	ds_read_b128 v[74:77], v118 offset:16384
	ds_read_b128 v[78:81], v118 offset:20480
	ds_read_b64_tr_b16 v[82:83], v114 offset:4096
	ds_read_b64_tr_b16 v[84:85], v115 offset:4096
	ds_read_b64_tr_b16 v[86:87], v116 offset:4096
	ds_read_b64_tr_b16 v[88:89], v117 offset:4096
	ds_read_b128 v[90:93], v119 offset:16384
	ds_read_b128 v[94:97], v119 offset:20480
	s_add_u32 m0, s38, 0x8000
	s_nop 0
	global_load_lds_dwordx4 v[98:99], off
	v_lshl_add_u64 v[98:99], v[98:99], 0, s[28:29]
	s_add_u32 m0, s38, 0x8400
	s_nop 0
	global_load_lds_dwordx4 v[100:101], off
	v_lshl_add_u64 v[100:101], v[100:101], 0, s[28:29]
	s_waitcnt lgkmcnt(6)
	v_mfma_f32_32x32x16_bf16 v[50:65], v[66:69], v[74:77], v[50:65]
	v_mfma_f32_32x32x16_bf16 v[34:49], v[66:69], v[78:81], v[34:49]
	v_mfma_f32_32x32x16_bf16 v[18:33], v[70:73], v[74:77], v[18:33]
	v_mfma_f32_32x32x16_bf16 v[2:17], v[70:73], v[78:81], v[2:17]
	ds_read_b64_tr_b16 v[66:67], v114 offset:8192
	ds_read_b64_tr_b16 v[68:69], v115 offset:8192
	ds_read_b64_tr_b16 v[70:71], v116 offset:8192
	ds_read_b64_tr_b16 v[72:73], v117 offset:8192
	ds_read_b128 v[74:77], v120 offset:16384
	ds_read_b128 v[78:81], v120 offset:20480
	s_add_u32 m0, s38, 0x8800
	s_nop 0
	global_load_lds_dwordx4 v[102:103], off
	v_lshl_add_u64 v[102:103], v[102:103], 0, s[28:29]
	s_add_u32 m0, s38, 0x8c00
	s_nop 0
	global_load_lds_dwordx4 v[104:105], off
	v_lshl_add_u64 v[104:105], v[104:105], 0, s[28:29]
	s_waitcnt lgkmcnt(6)
	v_mfma_f32_32x32x16_bf16 v[50:65], v[82:85], v[90:93], v[50:65]
	v_mfma_f32_32x32x16_bf16 v[34:49], v[82:85], v[94:97], v[34:49]
	v_mfma_f32_32x32x16_bf16 v[18:33], v[86:89], v[90:93], v[18:33]
	v_mfma_f32_32x32x16_bf16 v[2:17], v[86:89], v[94:97], v[2:17]
	ds_read_b64_tr_b16 v[82:83], v114 offset:12288
	ds_read_b64_tr_b16 v[84:85], v115 offset:12288
	ds_read_b64_tr_b16 v[86:87], v116 offset:12288
	ds_read_b64_tr_b16 v[88:89], v117 offset:12288
	ds_read_b128 v[90:93], v121 offset:16384
	ds_read_b128 v[94:97], v121 offset:20480
	s_add_u32 m0, s38, 0xc010
	s_nop 0
	global_load_lds_dwordx4 v[106:107], off
	v_lshl_add_u64 v[106:107], v[106:107], 0, s[36:37]
	s_add_u32 m0, s38, 0xc410
	s_nop 0
	global_load_lds_dwordx4 v[108:109], off
	v_lshl_add_u64 v[108:109], v[108:109], 0, s[36:37]
	s_waitcnt lgkmcnt(6)
	v_mfma_f32_32x32x16_bf16 v[50:65], v[66:69], v[74:77], v[50:65]
	v_mfma_f32_32x32x16_bf16 v[34:49], v[66:69], v[78:81], v[34:49]
	v_mfma_f32_32x32x16_bf16 v[18:33], v[70:73], v[74:77], v[18:33]
	v_mfma_f32_32x32x16_bf16 v[2:17], v[70:73], v[78:81], v[2:17]
	s_add_u32 m0, s38, 0xc810
	s_nop 0
	global_load_lds_dwordx4 v[110:111], off
	v_lshl_add_u64 v[110:111], v[110:111], 0, s[36:37]
	s_add_u32 m0, s38, 0xcc10
	s_nop 0
	global_load_lds_dwordx4 v[112:113], off
	v_lshl_add_u64 v[112:113], v[112:113], 0, s[36:37]
	s_waitcnt lgkmcnt(0)
	v_mfma_f32_32x32x16_bf16 v[50:65], v[82:85], v[90:93], v[50:65]
	v_mfma_f32_32x32x16_bf16 v[34:49], v[82:85], v[94:97], v[34:49]
	v_mfma_f32_32x32x16_bf16 v[18:33], v[86:89], v[90:93], v[18:33]
	v_mfma_f32_32x32x16_bf16 v[2:17], v[86:89], v[94:97], v[2:17]
	s_waitcnt vmcnt(0)
	s_barrier
	ds_read_b64_tr_b16 v[66:67], v114 offset:32768
	ds_read_b64_tr_b16 v[68:69], v115 offset:32768
	ds_read_b64_tr_b16 v[70:71], v116 offset:32768
	ds_read_b64_tr_b16 v[72:73], v117 offset:32768
	ds_read_b128 v[74:77], v118 offset:49168
	ds_read_b128 v[78:81], v118 offset:53264
	ds_read_b64_tr_b16 v[82:83], v114 offset:36864
	ds_read_b64_tr_b16 v[84:85], v115 offset:36864
	ds_read_b64_tr_b16 v[86:87], v116 offset:36864
	ds_read_b64_tr_b16 v[88:89], v117 offset:36864
	ds_read_b128 v[90:93], v119 offset:49168
	ds_read_b128 v[94:97], v119 offset:53264
	s_add_u32 m0, s38, 0x0
	s_nop 0
	global_load_lds_dwordx4 v[98:99], off
	v_lshl_add_u64 v[98:99], v[98:99], 0, s[28:29]
	s_add_u32 m0, s38, 0x400
	s_nop 0
	global_load_lds_dwordx4 v[100:101], off
	v_lshl_add_u64 v[100:101], v[100:101], 0, s[28:29]
	s_waitcnt lgkmcnt(6)
	v_mfma_f32_32x32x16_bf16 v[50:65], v[66:69], v[74:77], v[50:65]
	v_mfma_f32_32x32x16_bf16 v[34:49], v[66:69], v[78:81], v[34:49]
	v_mfma_f32_32x32x16_bf16 v[18:33], v[70:73], v[74:77], v[18:33]
	v_mfma_f32_32x32x16_bf16 v[2:17], v[70:73], v[78:81], v[2:17]
	ds_read_b64_tr_b16 v[66:67], v114 offset:40960
	ds_read_b64_tr_b16 v[68:69], v115 offset:40960
	ds_read_b64_tr_b16 v[70:71], v116 offset:40960
	ds_read_b64_tr_b16 v[72:73], v117 offset:40960
	ds_read_b128 v[74:77], v120 offset:49168
	ds_read_b128 v[78:81], v120 offset:53264
	s_add_u32 m0, s38, 0x800
	s_nop 0
	global_load_lds_dwordx4 v[102:103], off
	v_lshl_add_u64 v[102:103], v[102:103], 0, s[28:29]
	s_add_u32 m0, s38, 0xc00
	s_nop 0
	global_load_lds_dwordx4 v[104:105], off
	v_lshl_add_u64 v[104:105], v[104:105], 0, s[28:29]
	s_waitcnt lgkmcnt(6)
	v_mfma_f32_32x32x16_bf16 v[50:65], v[82:85], v[90:93], v[50:65]
	v_mfma_f32_32x32x16_bf16 v[34:49], v[82:85], v[94:97], v[34:49]
	v_mfma_f32_32x32x16_bf16 v[18:33], v[86:89], v[90:93], v[18:33]
	v_mfma_f32_32x32x16_bf16 v[2:17], v[86:89], v[94:97], v[2:17]
	ds_read_b64_tr_b16 v[82:83], v114 offset:45056
	ds_read_b64_tr_b16 v[84:85], v115 offset:45056
	ds_read_b64_tr_b16 v[86:87], v116 offset:45056
	ds_read_b64_tr_b16 v[88:89], v117 offset:45056
	ds_read_b128 v[90:93], v121 offset:49168
	ds_read_b128 v[94:97], v121 offset:53264
	s_add_u32 m0, s38, 0x4000
	s_nop 0
	global_load_lds_dwordx4 v[106:107], off
	v_lshl_add_u64 v[106:107], v[106:107], 0, s[36:37]
	s_add_u32 m0, s38, 0x4400
	s_nop 0
	global_load_lds_dwordx4 v[108:109], off
	v_lshl_add_u64 v[108:109], v[108:109], 0, s[36:37]
	s_waitcnt lgkmcnt(6)
	v_mfma_f32_32x32x16_bf16 v[50:65], v[66:69], v[74:77], v[50:65]
	v_mfma_f32_32x32x16_bf16 v[34:49], v[66:69], v[78:81], v[34:49]
	v_mfma_f32_32x32x16_bf16 v[18:33], v[70:73], v[74:77], v[18:33]
	v_mfma_f32_32x32x16_bf16 v[2:17], v[70:73], v[78:81], v[2:17]
	s_add_u32 m0, s38, 0x4800
	s_nop 0
	global_load_lds_dwordx4 v[110:111], off
	v_lshl_add_u64 v[110:111], v[110:111], 0, s[36:37]
	s_add_u32 m0, s38, 0x4c00
	s_nop 0
	global_load_lds_dwordx4 v[112:113], off
	v_lshl_add_u64 v[112:113], v[112:113], 0, s[36:37]
	s_waitcnt lgkmcnt(0)
	v_mfma_f32_32x32x16_bf16 v[50:65], v[82:85], v[90:93], v[50:65]
	v_mfma_f32_32x32x16_bf16 v[34:49], v[82:85], v[94:97], v[34:49]
	v_mfma_f32_32x32x16_bf16 v[18:33], v[86:89], v[90:93], v[18:33]
	v_mfma_f32_32x32x16_bf16 v[2:17], v[86:89], v[94:97], v[2:17]
	s_sub_u32 s100, s100, 1
	s_cmp_lg_u32 s100, 0
	s_cbranch_scc1 .LgemmT_p10_loop
	s_waitcnt vmcnt(0)
	s_barrier
	ds_read_b64_tr_b16 v[66:67], v114 offset:0
	ds_read_b64_tr_b16 v[68:69], v115 offset:0
	ds_read_b64_tr_b16 v[70:71], v116 offset:0
	ds_read_b64_tr_b16 v[72:73], v117 offset:0
	ds_read_b128 v[74:77], v118 offset:16384
	ds_read_b128 v[78:81], v118 offset:20480
	ds_read_b64_tr_b16 v[82:83], v114 offset:4096
	ds_read_b64_tr_b16 v[84:85], v115 offset:4096
	ds_read_b64_tr_b16 v[86:87], v116 offset:4096
	ds_read_b64_tr_b16 v[88:89], v117 offset:4096
	ds_read_b128 v[90:93], v119 offset:16384
	ds_read_b128 v[94:97], v119 offset:20480
	s_add_u32 m0, s38, 0x8000
	s_nop 0
	global_load_lds_dwordx4 v[98:99], off
	v_lshl_add_u64 v[98:99], v[98:99], 0, s[28:29]
	s_add_u32 m0, s38, 0x8400
	s_nop 0
	global_load_lds_dwordx4 v[100:101], off
	v_lshl_add_u64 v[100:101], v[100:101], 0, s[28:29]
	s_waitcnt lgkmcnt(6)
	v_mfma_f32_32x32x16_bf16 v[50:65], v[66:69], v[74:77], v[50:65]
	v_mfma_f32_32x32x16_bf16 v[34:49], v[66:69], v[78:81], v[34:49]
	v_mfma_f32_32x32x16_bf16 v[18:33], v[70:73], v[74:77], v[18:33]
	v_mfma_f32_32x32x16_bf16 v[2:17], v[70:73], v[78:81], v[2:17]
	ds_read_b64_tr_b16 v[66:67], v114 offset:8192
	ds_read_b64_tr_b16 v[68:69], v115 offset:8192
	ds_read_b64_tr_b16 v[70:71], v116 offset:8192
	ds_read_b64_tr_b16 v[72:73], v117 offset:8192
	ds_read_b128 v[74:77], v120 offset:16384
	ds_read_b128 v[78:81], v120 offset:20480
	s_add_u32 m0, s38, 0x8800
	s_nop 0
	global_load_lds_dwordx4 v[102:103], off
	v_lshl_add_u64 v[102:103], v[102:103], 0, s[28:29]
	s_add_u32 m0, s38, 0x8c00
	s_nop 0
	global_load_lds_dwordx4 v[104:105], off
	v_lshl_add_u64 v[104:105], v[104:105], 0, s[28:29]
	s_waitcnt lgkmcnt(6)
	v_mfma_f32_32x32x16_bf16 v[50:65], v[82:85], v[90:93], v[50:65]
	v_mfma_f32_32x32x16_bf16 v[34:49], v[82:85], v[94:97], v[34:49]
	v_mfma_f32_32x32x16_bf16 v[18:33], v[86:89], v[90:93], v[18:33]
	v_mfma_f32_32x32x16_bf16 v[2:17], v[86:89], v[94:97], v[2:17]
	ds_read_b64_tr_b16 v[82:83], v114 offset:12288
	ds_read_b64_tr_b16 v[84:85], v115 offset:12288
	ds_read_b64_tr_b16 v[86:87], v116 offset:12288
	ds_read_b64_tr_b16 v[88:89], v117 offset:12288
	ds_read_b128 v[90:93], v121 offset:16384
	ds_read_b128 v[94:97], v121 offset:20480
	s_add_u32 m0, s38, 0xc010
	s_nop 0
	global_load_lds_dwordx4 v[106:107], off
	v_lshl_add_u64 v[106:107], v[106:107], 0, s[36:37]
	s_add_u32 m0, s38, 0xc410
	s_nop 0
	global_load_lds_dwordx4 v[108:109], off
	v_lshl_add_u64 v[108:109], v[108:109], 0, s[36:37]
	s_waitcnt lgkmcnt(6)
	v_mfma_f32_32x32x16_bf16 v[50:65], v[66:69], v[74:77], v[50:65]
	v_mfma_f32_32x32x16_bf16 v[34:49], v[66:69], v[78:81], v[34:49]
	v_mfma_f32_32x32x16_bf16 v[18:33], v[70:73], v[74:77], v[18:33]
	v_mfma_f32_32x32x16_bf16 v[2:17], v[70:73], v[78:81], v[2:17]
	s_add_u32 m0, s38, 0xc810
	s_nop 0
	global_load_lds_dwordx4 v[110:111], off
	v_lshl_add_u64 v[110:111], v[110:111], 0, s[36:37]
	s_add_u32 m0, s38, 0xcc10
	s_nop 0
	global_load_lds_dwordx4 v[112:113], off
	v_lshl_add_u64 v[112:113], v[112:113], 0, s[36:37]
	s_waitcnt lgkmcnt(0)
	v_mfma_f32_32x32x16_bf16 v[50:65], v[82:85], v[90:93], v[50:65]
	v_mfma_f32_32x32x16_bf16 v[34:49], v[82:85], v[94:97], v[34:49]
	v_mfma_f32_32x32x16_bf16 v[18:33], v[86:89], v[90:93], v[18:33]
	v_mfma_f32_32x32x16_bf16 v[2:17], v[86:89], v[94:97], v[2:17]
	s_waitcnt vmcnt(0)
	s_barrier
	ds_read_b64_tr_b16 v[66:67], v114 offset:32768
	ds_read_b64_tr_b16 v[68:69], v115 offset:32768
	ds_read_b64_tr_b16 v[70:71], v116 offset:32768
	ds_read_b64_tr_b16 v[72:73], v117 offset:32768
	ds_read_b128 v[74:77], v118 offset:49168
	ds_read_b128 v[78:81], v118 offset:53264
	ds_read_b64_tr_b16 v[82:83], v114 offset:36864
	ds_read_b64_tr_b16 v[84:85], v115 offset:36864
	ds_read_b64_tr_b16 v[86:87], v116 offset:36864
	ds_read_b64_tr_b16 v[88:89], v117 offset:36864
	ds_read_b128 v[90:93], v119 offset:49168
	ds_read_b128 v[94:97], v119 offset:53264
	s_waitcnt lgkmcnt(6)
	v_mfma_f32_32x32x16_bf16 v[50:65], v[66:69], v[74:77], v[50:65]
	v_mfma_f32_32x32x16_bf16 v[34:49], v[66:69], v[78:81], v[34:49]
	v_mfma_f32_32x32x16_bf16 v[18:33], v[70:73], v[74:77], v[18:33]
	v_mfma_f32_32x32x16_bf16 v[2:17], v[70:73], v[78:81], v[2:17]
	ds_read_b64_tr_b16 v[66:67], v114 offset:40960
	ds_read_b64_tr_b16 v[68:69], v115 offset:40960
	ds_read_b64_tr_b16 v[70:71], v116 offset:40960
	ds_read_b64_tr_b16 v[72:73], v117 offset:40960
	ds_read_b128 v[74:77], v120 offset:49168
	ds_read_b128 v[78:81], v120 offset:53264
	s_waitcnt lgkmcnt(6)
	v_mfma_f32_32x32x16_bf16 v[50:65], v[82:85], v[90:93], v[50:65]
	v_mfma_f32_32x32x16_bf16 v[34:49], v[82:85], v[94:97], v[34:49]
	v_mfma_f32_32x32x16_bf16 v[18:33], v[86:89], v[90:93], v[18:33]
	v_mfma_f32_32x32x16_bf16 v[2:17], v[86:89], v[94:97], v[2:17]
	ds_read_b64_tr_b16 v[82:83], v114 offset:45056
	ds_read_b64_tr_b16 v[84:85], v115 offset:45056
	ds_read_b64_tr_b16 v[86:87], v116 offset:45056
	ds_read_b64_tr_b16 v[88:89], v117 offset:45056
	ds_read_b128 v[90:93], v121 offset:49168
	ds_read_b128 v[94:97], v121 offset:53264
	s_waitcnt lgkmcnt(6)
	v_mfma_f32_32x32x16_bf16 v[50:65], v[66:69], v[74:77], v[50:65]
	v_mfma_f32_32x32x16_bf16 v[34:49], v[66:69], v[78:81], v[34:49]
	v_mfma_f32_32x32x16_bf16 v[18:33], v[70:73], v[74:77], v[18:33]
	v_mfma_f32_32x32x16_bf16 v[2:17], v[70:73], v[78:81], v[2:17]
	s_waitcnt lgkmcnt(0)
	v_mfma_f32_32x32x16_bf16 v[50:65], v[82:85], v[90:93], v[50:65]
	v_mfma_f32_32x32x16_bf16 v[34:49], v[82:85], v[94:97], v[34:49]
	v_mfma_f32_32x32x16_bf16 v[18:33], v[86:89], v[90:93], v[18:33]
	v_mfma_f32_32x32x16_bf16 v[2:17], v[86:89], v[94:97], v[2:17]
	v_readlane_b32 s38, v248, 2
	v_readlane_b32 s39, v248, 3
	s_nop 3
	v_mov_b32_e32 v66, v184
	s_mov_b64 s[36:37], s[38:39]
	s_mov_b64 s[0:1], s[8:9]
	v_ashrrev_i32_e32 v1, 1, v66
	v_and_b32_e32 v1, 0xffffffc0, v1
	v_lshrrev_b32_e32 v67, 3, v66
	v_and_b32_e32 v67, 4, v67
	v_add_u32_e32 v1, s24, v1
	v_or_b32_e32 v1, v1, v67
	v_and_b32_e32 v68, 0x5f, v66
	v_or_b32_e32 v68, s23, v68
	v_lshlrev_b32_e32 v69, 2, v68
	v_lshl_add_u32 v70, v1, 12, v69
	s_add_i32 s28, s24, 0xffffe000
	s_ashr_i32 s28, s28, 12
	s_mulk_i32 s28, 0xc00
	s_addk_i32 s28, 0x800
	s_cmp_gt_i32 s22, 63
	s_cselect_b32 s28, s28, 0x6800
	v_add_lshl_u32 v71, v68, s28, 2
	v_mov_b32_e32 v74, v70
	v_add_u32_e32 v75, 0x1000, v70
	v_add_u32_e32 v76, 0x2000, v70
	v_add_u32_e32 v77, 0x3000, v70
	v_add_u32_e32 v78, 0x8000, v70
	v_add_u32_e32 v79, 0x9000, v70
	v_add_u32_e32 v80, 0xa000, v70
	v_add_u32_e32 v81, 0xb000, v70
	v_add_u32_e32 v82, 0x10000, v70
	v_add_u32_e32 v83, 0x11000, v70
	v_add_u32_e32 v84, 0x12000, v70
	v_add_u32_e32 v85, 0x13000, v70
	v_add_u32_e32 v86, 0x18000, v70
	v_add_u32_e32 v87, 0x19000, v70
	v_add_u32_e32 v88, 0x1a000, v70
	v_add_u32_e32 v89, 0x1b000, v70
	global_load_dword v122, v71, s[0:1]
	global_load_dword v123, v71, s[0:1] offset:128
	global_load_dword v90, v74, s[36:37] nt
	global_load_dword v91, v75, s[36:37] nt
	global_load_dword v92, v76, s[36:37] nt
	global_load_dword v93, v77, s[36:37] nt
	global_load_dword v94, v78, s[36:37] nt
	global_load_dword v95, v79, s[36:37] nt
	global_load_dword v96, v80, s[36:37] nt
	global_load_dword v97, v81, s[36:37] nt
	global_load_dword v98, v82, s[36:37] nt
	global_load_dword v99, v83, s[36:37] nt
	global_load_dword v100, v84, s[36:37] nt
	global_load_dword v101, v85, s[36:37] nt
	global_load_dword v102, v86, s[36:37] nt
	global_load_dword v103, v87, s[36:37] nt
	global_load_dword v104, v88, s[36:37] nt
	global_load_dword v105, v89, s[36:37] nt
	global_load_dword v106, v74, s[36:37] offset:128 nt
	global_load_dword v107, v75, s[36:37] offset:128 nt
	global_load_dword v108, v76, s[36:37] offset:128 nt
	global_load_dword v109, v77, s[36:37] offset:128 nt
	global_load_dword v110, v78, s[36:37] offset:128 nt
	global_load_dword v111, v79, s[36:37] offset:128 nt
	global_load_dword v112, v80, s[36:37] offset:128 nt
	global_load_dword v113, v81, s[36:37] offset:128 nt
	global_load_dword v114, v82, s[36:37] offset:128 nt
	global_load_dword v115, v83, s[36:37] offset:128 nt
	global_load_dword v116, v84, s[36:37] offset:128 nt
	global_load_dword v117, v85, s[36:37] offset:128 nt
	global_load_dword v118, v86, s[36:37] offset:128 nt
	global_load_dword v119, v87, s[36:37] offset:128 nt
	global_load_dword v120, v88, s[36:37] offset:128 nt
	global_load_dword v121, v89, s[36:37] offset:128 nt
	s_waitcnt vmcnt(31)
	v_fmac_f32_e32 v90, v50, v122
	global_store_dword v74, v90, s[38:39]
	s_waitcnt vmcnt(31)
	v_fmac_f32_e32 v91, v51, v122
	global_store_dword v75, v91, s[38:39]
	s_waitcnt vmcnt(31)
	v_fmac_f32_e32 v92, v52, v122
	global_store_dword v76, v92, s[38:39]
	s_waitcnt vmcnt(31)
	v_fmac_f32_e32 v93, v53, v122
	global_store_dword v77, v93, s[38:39]
	s_waitcnt vmcnt(31)
	v_fmac_f32_e32 v94, v54, v122
	global_store_dword v78, v94, s[38:39]
	s_waitcnt vmcnt(31)
	v_fmac_f32_e32 v95, v55, v122
	global_store_dword v79, v95, s[38:39]
	s_waitcnt vmcnt(31)
	v_fmac_f32_e32 v96, v56, v122
	global_store_dword v80, v96, s[38:39]
	s_waitcnt vmcnt(31)
	v_fmac_f32_e32 v97, v57, v122
	global_store_dword v81, v97, s[38:39]
	s_waitcnt vmcnt(31)
	v_fmac_f32_e32 v98, v58, v122
	global_store_dword v82, v98, s[38:39]
	s_waitcnt vmcnt(31)
	v_fmac_f32_e32 v99, v59, v122
	global_store_dword v83, v99, s[38:39]
	s_waitcnt vmcnt(31)
	v_fmac_f32_e32 v100, v60, v122
	global_store_dword v84, v100, s[38:39]
	s_waitcnt vmcnt(31)
	v_fmac_f32_e32 v101, v61, v122
	global_store_dword v85, v101, s[38:39]
	s_waitcnt vmcnt(31)
	v_fmac_f32_e32 v102, v62, v122
	global_store_dword v86, v102, s[38:39]
	s_waitcnt vmcnt(31)
	v_fmac_f32_e32 v103, v63, v122
	global_store_dword v87, v103, s[38:39]
	s_waitcnt vmcnt(31)
	v_fmac_f32_e32 v104, v64, v122
	global_store_dword v88, v104, s[38:39]
	s_waitcnt vmcnt(31)
	v_fmac_f32_e32 v105, v65, v122
	global_store_dword v89, v105, s[38:39]
	v_add_u32_e32 v50, 0x20000, v74
	v_add_u32_e32 v51, 0x20000, v75
	v_add_u32_e32 v52, 0x20000, v76
	v_add_u32_e32 v53, 0x20000, v77
	v_add_u32_e32 v54, 0x20000, v78
	v_add_u32_e32 v55, 0x20000, v79
	v_add_u32_e32 v56, 0x20000, v80
	v_add_u32_e32 v57, 0x20000, v81
	v_add_u32_e32 v58, 0x20000, v82
	v_add_u32_e32 v59, 0x20000, v83
	v_add_u32_e32 v60, 0x20000, v84
	v_add_u32_e32 v61, 0x20000, v85
	v_add_u32_e32 v62, 0x20000, v86
	v_add_u32_e32 v63, 0x20000, v87
	v_add_u32_e32 v64, 0x20000, v88
	v_add_u32_e32 v65, 0x20000, v89
	global_load_dword v90, v50, s[36:37] nt
	global_load_dword v91, v51, s[36:37] nt
	global_load_dword v92, v52, s[36:37] nt
	global_load_dword v93, v53, s[36:37] nt
	global_load_dword v94, v54, s[36:37] nt
	global_load_dword v95, v55, s[36:37] nt
	global_load_dword v96, v56, s[36:37] nt
	global_load_dword v97, v57, s[36:37] nt
	global_load_dword v98, v58, s[36:37] nt
	global_load_dword v99, v59, s[36:37] nt
	global_load_dword v100, v60, s[36:37] nt
	global_load_dword v101, v61, s[36:37] nt
	global_load_dword v102, v62, s[36:37] nt
	global_load_dword v103, v63, s[36:37] nt
	global_load_dword v104, v64, s[36:37] nt
	global_load_dword v105, v65, s[36:37] nt
	s_waitcnt vmcnt(47)
	v_fmac_f32_e32 v106, v34, v123
	global_store_dword v74, v106, s[38:39] offset:128
	s_waitcnt vmcnt(47)
	v_fmac_f32_e32 v107, v35, v123
	global_store_dword v75, v107, s[38:39] offset:128
	s_waitcnt vmcnt(47)
	v_fmac_f32_e32 v108, v36, v123
	global_store_dword v76, v108, s[38:39] offset:128
	s_waitcnt vmcnt(47)
	v_fmac_f32_e32 v109, v37, v123
	global_store_dword v77, v109, s[38:39] offset:128
	s_waitcnt vmcnt(47)
	v_fmac_f32_e32 v110, v38, v123
	global_store_dword v78, v110, s[38:39] offset:128
	s_waitcnt vmcnt(47)
	v_fmac_f32_e32 v111, v39, v123
	global_store_dword v79, v111, s[38:39] offset:128
	s_waitcnt vmcnt(47)
	v_fmac_f32_e32 v112, v40, v123
	global_store_dword v80, v112, s[38:39] offset:128
	s_waitcnt vmcnt(47)
	v_fmac_f32_e32 v113, v41, v123
	global_store_dword v81, v113, s[38:39] offset:128
	s_waitcnt vmcnt(47)
	v_fmac_f32_e32 v114, v42, v123
	global_store_dword v82, v114, s[38:39] offset:128
	s_waitcnt vmcnt(47)
	v_fmac_f32_e32 v115, v43, v123
	global_store_dword v83, v115, s[38:39] offset:128
	s_waitcnt vmcnt(47)
	v_fmac_f32_e32 v116, v44, v123
	global_store_dword v84, v116, s[38:39] offset:128
	s_waitcnt vmcnt(47)
	v_fmac_f32_e32 v117, v45, v123
	global_store_dword v85, v117, s[38:39] offset:128
	s_waitcnt vmcnt(47)
	v_fmac_f32_e32 v118, v46, v123
	global_store_dword v86, v118, s[38:39] offset:128
	s_waitcnt vmcnt(47)
	v_fmac_f32_e32 v119, v47, v123
	global_store_dword v87, v119, s[38:39] offset:128
	s_waitcnt vmcnt(47)
	v_fmac_f32_e32 v120, v48, v123
	global_store_dword v88, v120, s[38:39] offset:128
	s_waitcnt vmcnt(47)
	v_fmac_f32_e32 v121, v49, v123
	global_store_dword v89, v121, s[38:39] offset:128
	global_load_dword v106, v50, s[36:37] offset:128 nt
	global_load_dword v107, v51, s[36:37] offset:128 nt
	global_load_dword v108, v52, s[36:37] offset:128 nt
	global_load_dword v109, v53, s[36:37] offset:128 nt
	global_load_dword v110, v54, s[36:37] offset:128 nt
	global_load_dword v111, v55, s[36:37] offset:128 nt
	global_load_dword v112, v56, s[36:37] offset:128 nt
	global_load_dword v113, v57, s[36:37] offset:128 nt
	global_load_dword v114, v58, s[36:37] offset:128 nt
	global_load_dword v115, v59, s[36:37] offset:128 nt
	global_load_dword v116, v60, s[36:37] offset:128 nt
	global_load_dword v117, v61, s[36:37] offset:128 nt
	global_load_dword v118, v62, s[36:37] offset:128 nt
	global_load_dword v119, v63, s[36:37] offset:128 nt
	global_load_dword v120, v64, s[36:37] offset:128 nt
	global_load_dword v121, v65, s[36:37] offset:128 nt
	s_waitcnt vmcnt(47)
	v_fmac_f32_e32 v90, v18, v122
	global_store_dword v50, v90, s[38:39]
	s_waitcnt vmcnt(47)
	v_fmac_f32_e32 v91, v19, v122
	global_store_dword v51, v91, s[38:39]
	s_waitcnt vmcnt(47)
	v_fmac_f32_e32 v92, v20, v122
	global_store_dword v52, v92, s[38:39]
	s_waitcnt vmcnt(47)
	v_fmac_f32_e32 v93, v21, v122
	global_store_dword v53, v93, s[38:39]
	s_waitcnt vmcnt(47)
	v_fmac_f32_e32 v94, v22, v122
	global_store_dword v54, v94, s[38:39]
	s_waitcnt vmcnt(47)
	v_fmac_f32_e32 v95, v23, v122
	global_store_dword v55, v95, s[38:39]
	s_waitcnt vmcnt(47)
	v_fmac_f32_e32 v96, v24, v122
	global_store_dword v56, v96, s[38:39]
	s_waitcnt vmcnt(47)
	v_fmac_f32_e32 v97, v25, v122
	global_store_dword v57, v97, s[38:39]
	s_waitcnt vmcnt(47)
	v_fmac_f32_e32 v98, v26, v122
	global_store_dword v58, v98, s[38:39]
	s_waitcnt vmcnt(47)
	v_fmac_f32_e32 v99, v27, v122
	global_store_dword v59, v99, s[38:39]
	s_waitcnt vmcnt(47)
	v_fmac_f32_e32 v100, v28, v122
	global_store_dword v60, v100, s[38:39]
	s_waitcnt vmcnt(47)
	v_fmac_f32_e32 v101, v29, v122
	global_store_dword v61, v101, s[38:39]
	s_waitcnt vmcnt(47)
	v_fmac_f32_e32 v102, v30, v122
	global_store_dword v62, v102, s[38:39]
	s_waitcnt vmcnt(47)
	v_fmac_f32_e32 v103, v31, v122
	global_store_dword v63, v103, s[38:39]
	s_waitcnt vmcnt(47)
	v_fmac_f32_e32 v104, v32, v122
	global_store_dword v64, v104, s[38:39]
	s_waitcnt vmcnt(47)
	v_fmac_f32_e32 v105, v33, v122
	global_store_dword v65, v105, s[38:39]
	s_waitcnt vmcnt(31)
	v_fmac_f32_e32 v106, v2, v123
	global_store_dword v50, v106, s[38:39] offset:128
	s_waitcnt vmcnt(31)
	v_fmac_f32_e32 v107, v3, v123
	global_store_dword v51, v107, s[38:39] offset:128
	s_waitcnt vmcnt(31)
	v_fmac_f32_e32 v108, v4, v123
	global_store_dword v52, v108, s[38:39] offset:128
	s_waitcnt vmcnt(31)
	v_fmac_f32_e32 v109, v5, v123
	global_store_dword v53, v109, s[38:39] offset:128
	s_waitcnt vmcnt(31)
	v_fmac_f32_e32 v110, v6, v123
	global_store_dword v54, v110, s[38:39] offset:128
	s_waitcnt vmcnt(31)
	v_fmac_f32_e32 v111, v7, v123
	global_store_dword v55, v111, s[38:39] offset:128
	s_waitcnt vmcnt(31)
	v_fmac_f32_e32 v112, v8, v123
	global_store_dword v56, v112, s[38:39] offset:128
	s_waitcnt vmcnt(31)
	v_fmac_f32_e32 v113, v9, v123
	global_store_dword v57, v113, s[38:39] offset:128
	s_waitcnt vmcnt(31)
	v_fmac_f32_e32 v114, v10, v123
	global_store_dword v58, v114, s[38:39] offset:128
	s_waitcnt vmcnt(31)
	v_fmac_f32_e32 v115, v11, v123
	global_store_dword v59, v115, s[38:39] offset:128
	s_waitcnt vmcnt(31)
	v_fmac_f32_e32 v116, v12, v123
	global_store_dword v60, v116, s[38:39] offset:128
	s_waitcnt vmcnt(31)
	v_fmac_f32_e32 v117, v13, v123
	global_store_dword v61, v117, s[38:39] offset:128
	s_waitcnt vmcnt(31)
	v_fmac_f32_e32 v118, v14, v123
	global_store_dword v62, v118, s[38:39] offset:128
	s_waitcnt vmcnt(31)
	v_fmac_f32_e32 v119, v15, v123
	global_store_dword v63, v119, s[38:39] offset:128
	s_waitcnt vmcnt(31)
	v_fmac_f32_e32 v120, v16, v123
	global_store_dword v64, v120, s[38:39] offset:128
	s_waitcnt vmcnt(31)
	v_fmac_f32_e32 v121, v17, v123
	global_store_dword v65, v121, s[38:39] offset:128
	v_readlane_b32 s0, v246, 1
	s_nop 1
	s_add_i32 s2, s2, s0
	s_cmpk_gt_i32 s2, 0x13f
	s_cbranch_scc0 .LBB0_89

.LBB0_599:
	s_ashr_i32 s0, s2, 31
	s_lshr_b32 s0, s0, 26
	s_add_i32 s0, s2, s0
	s_andn2_b32 s0, s0, 63
	s_sub_i32 s1, s2, s0
	s_bfe_i32 s22, s1, 0x80000
	s_bfe_u32 s22, s22, 0x3000c
	s_add_i32 s23, s1, s22
	s_bfe_i32 s22, s23, 0x80000
	s_sext_i32_i16 s22, s22
	s_and_b32 s22, s22, -8
	s_add_i32 s22, s22, s0
	v_readlane_b32 s0, v246, 0
	s_or_b32 s22, s22, s0
	s_and_b32 s0, s23, 0xf8
	s_sub_i32 s0, s1, s0
	s_sext_i32_i8 s0, s0
	s_lshl_b32 s23, s0, 7
	v_readlane_b32 s0, v246, 22
	s_lshl_b32 s24, s22, 7
	s_barrier
	v_lshrrev_b32_e32 v122, 6, v184
	v_and_b32_e32 v123, 63, v184
	v_readfirstlane_b32 s39, v122
	v_lshrrev_b32_e32 v124, 4, v123
	v_and_b32_e32 v125, 15, v123
	v_lshlrev_b32_e32 v126, 2, v124
	v_xor_b32_e32 v125, v125, v126
	v_mul_u32_u24_e32 v124, 0x14000, v124
	v_readlane_b32 s0, v246, 22
	v_readlane_b32 s1, v246, 23
	s_nop 3
	s_lshl_b32 s38, s39, 12
	s_mul_i32 s100, s39, 0x140000
	s_lshl_b32 s28, s24, 1
	s_add_u32 s100, s100, s28
	s_add_u32 s100, s100, 0xb04a000
	s_add_u32 s28, s68, s100
	s_addc_u32 s29, s69, 0
	v_xor_b32_e32 v126, 0, v125
	v_lshl_add_u32 v126, v126, 4, v124
	v_mov_b32_e32 v127, 0
	v_lshl_add_u64 v[98:99], v[126:127], 0, s[28:29]
	s_add_u32 s28, s28, 0x50000
	s_addc_u32 s29, s29, 0
	v_xor_b32_e32 v126, 1, v125
	v_lshl_add_u32 v126, v126, 4, v124
	v_mov_b32_e32 v127, 0
	v_lshl_add_u64 v[100:101], v[126:127], 0, s[28:29]
	s_add_u32 s28, s28, 0x50000
	s_addc_u32 s29, s29, 0
	v_xor_b32_e32 v126, 2, v125
	v_lshl_add_u32 v126, v126, 4, v124
	v_mov_b32_e32 v127, 0
	v_lshl_add_u64 v[102:103], v[126:127], 0, s[28:29]
	s_add_u32 s28, s28, 0x50000
	s_addc_u32 s29, s29, 0
	v_xor_b32_e32 v126, 3, v125
	v_lshl_add_u32 v126, v126, 4, v124
	v_mov_b32_e32 v127, 0
	v_lshl_add_u64 v[104:105], v[126:127], 0, s[28:29]
	v_lshrrev_b32_e32 v124, 3, v123
	v_lshrrev_b32_e32 v125, 4, v123
	v_and_b32_e32 v126, 7, v123
	s_lshl_b32 s100, s39, 5
	s_add_i32 s100, s100, s23
	s_lshl_b32 s100, s100, 11
	s_add_u32 s0, s0, s100
	s_addc_u32 s1, s1, 0
	v_and_b32_e32 v127, 7, v125
	v_xor_b32_e32 v127, v126, v127
	v_lshlrev_b32_e32 v127, 4, v127
	v_lshl_add_u32 v128, v124, 11, v127
	v_mov_b32_e32 v96, v128
	v_mov_b32_e32 v97, 0
	v_lshl_add_u64 v[106:107], v[96:97], 0, s[0:1]
	s_add_u32 s0, s0, 0x4000
	s_addc_u32 s1, s1, 0
	v_add_u32_e32 v127, 4, v125
	v_and_b32_e32 v127, 7, v127
	v_xor_b32_e32 v127, v126, v127
	v_lshlrev_b32_e32 v127, 4, v127
	v_lshl_add_u32 v128, v124, 11, v127
	v_mov_b32_e32 v96, v128
	v_mov_b32_e32 v97, 0
	v_lshl_add_u64 v[108:109], v[96:97], 0, s[0:1]
	s_add_u32 s0, s0, 0x4000
	s_addc_u32 s1, s1, 0
	v_and_b32_e32 v127, 7, v125
	v_xor_b32_e32 v127, v126, v127
	v_lshlrev_b32_e32 v127, 4, v127
	v_lshl_add_u32 v128, v124, 11, v127
	v_mov_b32_e32 v96, v128
	v_mov_b32_e32 v97, 0
	v_lshl_add_u64 v[110:111], v[96:97], 0, s[0:1]
	s_add_u32 s0, s0, 0x4000
	s_addc_u32 s1, s1, 0
	v_add_u32_e32 v127, 4, v125
	v_and_b32_e32 v127, 7, v127
	v_xor_b32_e32 v127, v126, v127
	v_lshlrev_b32_e32 v127, 4, v127
	v_lshl_add_u32 v128, v124, 11, v127
	v_mov_b32_e32 v96, v128
	v_mov_b32_e32 v97, 0
	v_lshl_add_u64 v[112:113], v[96:97], 0, s[0:1]
	s_mov_b32 s28, 0x500000
	s_mov_b32 s29, 0
	s_mov_b32 s36, 128
	s_mov_b32 s37, 0
	s_add_u32 m0, s38, 0x0
	s_nop 0
	global_load_lds_dwordx4 v[98:99], off
	v_lshl_add_u64 v[98:99], v[98:99], 0, s[28:29]
	s_add_u32 m0, s38, 0x400
	s_nop 0
	global_load_lds_dwordx4 v[100:101], off
	v_lshl_add_u64 v[100:101], v[100:101], 0, s[28:29]
	s_add_u32 m0, s38, 0x800
	s_nop 0
	global_load_lds_dwordx4 v[102:103], off
	v_lshl_add_u64 v[102:103], v[102:103], 0, s[28:29]
	s_add_u32 m0, s38, 0xc00
	s_nop 0
	global_load_lds_dwordx4 v[104:105], off
	v_lshl_add_u64 v[104:105], v[104:105], 0, s[28:29]
	s_add_u32 m0, s38, 0x4000
	s_nop 0
	global_load_lds_dwordx4 v[106:107], off
	v_lshl_add_u64 v[106:107], v[106:107], 0, s[36:37]
	s_add_u32 m0, s38, 0x4400
	s_nop 0
	global_load_lds_dwordx4 v[108:109], off
	v_lshl_add_u64 v[108:109], v[108:109], 0, s[36:37]
	s_add_u32 m0, s38, 0x4800
	s_nop 0
	global_load_lds_dwordx4 v[110:111], off
	v_lshl_add_u64 v[110:111], v[110:111], 0, s[36:37]
	s_add_u32 m0, s38, 0x4c00
	s_nop 0
	global_load_lds_dwordx4 v[112:113], off
	v_lshl_add_u64 v[112:113], v[112:113], 0, s[36:37]
	v_and_b32_e32 v122, 31, v123
	v_lshrrev_b32_e32 v124, 5, v123
	v_bfe_u32 v125, v123, 4, 1
	v_bfe_u32 v126, v123, 2, 2
	v_and_b32_e32 v127, 3, v123
	s_lshr_b32 s101, s39, 1
	s_and_b32 s39, s39, 1
	v_lshlrev_b32_e32 v96, 1, v124
	v_add_u32_e32 v96, 0, v96
	v_and_b32_e32 v96, 3, v96
	v_lshl_or_b32 v96, v126, 2, v96
	v_lshrrev_b32_e32 v97, 1, v127
	v_lshl_or_b32 v97, v125, 1, v97
	v_or_b32_e32 v97, 0, v97
	s_lshl_b32 s0, s101, 3
	v_or_b32_e32 v97, s0, v97
	v_xor_b32_e32 v97, v97, v96
	v_lshlrev_b32_e32 v96, 3, v124
	v_add3_u32 v96, v96, v126, 0
	v_lshlrev_b32_e32 v96, 8, v96
	v_lshl_add_u32 v96, v97, 4, v96
	v_and_b32_e32 v97, 1, v127
	v_lshl_add_u32 v114, v97, 3, v96
	v_lshlrev_b32_e32 v96, 1, v124
	v_add_u32_e32 v96, 1, v96
	v_and_b32_e32 v96, 3, v96
	v_lshl_or_b32 v96, v126, 2, v96
	v_lshrrev_b32_e32 v97, 1, v127
	v_lshl_or_b32 v97, v125, 1, v97
	v_or_b32_e32 v97, 0, v97
	s_lshl_b32 s0, s101, 3
	v_or_b32_e32 v97, s0, v97
	v_xor_b32_e32 v97, v97, v96
	v_lshlrev_b32_e32 v96, 3, v124
	v_add3_u32 v96, v96, v126, 4
	v_lshlrev_b32_e32 v96, 8, v96
	v_lshl_add_u32 v96, v97, 4, v96
	v_and_b32_e32 v97, 1, v127
	v_lshl_add_u32 v115, v97, 3, v96
	v_lshlrev_b32_e32 v96, 1, v124
	v_add_u32_e32 v96, 0, v96
	v_and_b32_e32 v96, 3, v96
	v_lshl_or_b32 v96, v126, 2, v96
	v_lshrrev_b32_e32 v97, 1, v127
	v_lshl_or_b32 v97, v125, 1, v97
	v_or_b32_e32 v97, 4, v97
	s_lshl_b32 s0, s101, 3
	v_or_b32_e32 v97, s0, v97
	v_xor_b32_e32 v97, v97, v96
	v_lshlrev_b32_e32 v96, 3, v124
	v_add3_u32 v96, v96, v126, 0
	v_lshlrev_b32_e32 v96, 8, v96
	v_lshl_add_u32 v96, v97, 4, v96
	v_and_b32_e32 v97, 1, v127
	v_lshl_add_u32 v116, v97, 3, v96
	v_lshlrev_b32_e32 v96, 1, v124
	v_add_u32_e32 v96, 1, v96
	v_and_b32_e32 v96, 3, v96
	v_lshl_or_b32 v96, v126, 2, v96
	v_lshrrev_b32_e32 v97, 1, v127
	v_lshl_or_b32 v97, v125, 1, v97
	v_or_b32_e32 v97, 4, v97
	s_lshl_b32 s0, s101, 3
	v_or_b32_e32 v97, s0, v97
	v_xor_b32_e32 v97, v97, v96
	v_lshlrev_b32_e32 v96, 3, v124
	v_add3_u32 v96, v96, v126, 4
	v_lshlrev_b32_e32 v96, 8, v96
	v_lshl_add_u32 v96, v97, 4, v96
	v_and_b32_e32 v97, 1, v127
	v_lshl_add_u32 v117, v97, 3, v96
	v_bfe_u32 v96, v122, 1, 3
	v_xor_b32_e32 v96, v96, v124
	v_lshlrev_b32_e32 v96, 4, v96
	v_lshl_add_u32 v96, v122, 7, v96
	s_lshl_b32 s0, s39, 13
	v_add_u32_e32 v118, s0, v96
	v_xor_b32_e32 v119, 0x20, v118
	v_xor_b32_e32 v120, 0x40, v118
	v_xor_b32_e32 v121, 0x60, v118
	v_mov_b32_e32 v2, 0
	v_mov_b32_e32 v3, v2
	v_mov_b32_e32 v4, v2
	v_mov_b32_e32 v5, v2
	v_mov_b32_e32 v6, v2
	v_mov_b32_e32 v7, v2
	v_mov_b32_e32 v8, v2
	v_mov_b32_e32 v9, v2
	v_mov_b32_e32 v10, v2
	v_mov_b32_e32 v11, v2
	v_mov_b32_e32 v12, v2
	v_mov_b32_e32 v13, v2
	v_mov_b32_e32 v14, v2
	v_mov_b32_e32 v15, v2
	v_mov_b32_e32 v16, v2
	v_mov_b32_e32 v17, v2
	v_mov_b32_e32 v18, v2
	v_mov_b32_e32 v19, v2
	v_mov_b32_e32 v20, v2
	v_mov_b32_e32 v21, v2
	v_mov_b32_e32 v22, v2
	v_mov_b32_e32 v23, v2
	v_mov_b32_e32 v24, v2
	v_mov_b32_e32 v25, v2
	v_mov_b32_e32 v26, v2
	v_mov_b32_e32 v27, v2
	v_mov_b32_e32 v28, v2
	v_mov_b32_e32 v29, v2
	v_mov_b32_e32 v30, v2
	v_mov_b32_e32 v31, v2
	v_mov_b32_e32 v32, v2
	v_mov_b32_e32 v33, v2
	v_mov_b32_e32 v34, v2
	v_mov_b32_e32 v35, v2
	v_mov_b32_e32 v36, v2
	v_mov_b32_e32 v37, v2
	v_mov_b32_e32 v38, v2
	v_mov_b32_e32 v39, v2
	v_mov_b32_e32 v40, v2
	v_mov_b32_e32 v41, v2
	v_mov_b32_e32 v42, v2
	v_mov_b32_e32 v43, v2
	v_mov_b32_e32 v44, v2
	v_mov_b32_e32 v45, v2
	v_mov_b32_e32 v46, v2
	v_mov_b32_e32 v47, v2
	v_mov_b32_e32 v48, v2
	v_mov_b32_e32 v49, v2
	v_mov_b32_e32 v50, v2
	v_mov_b32_e32 v51, v2
	v_mov_b32_e32 v52, v2
	v_mov_b32_e32 v53, v2
	v_mov_b32_e32 v54, v2
	v_mov_b32_e32 v55, v2
	v_mov_b32_e32 v56, v2
	v_mov_b32_e32 v57, v2
	v_mov_b32_e32 v58, v2
	v_mov_b32_e32 v59, v2
	v_mov_b32_e32 v60, v2
	v_mov_b32_e32 v61, v2
	v_mov_b32_e32 v62, v2
	v_mov_b32_e32 v63, v2
	v_mov_b32_e32 v64, v2
	v_mov_b32_e32 v65, v2
	s_mov_b32 s100, 7
.LgemmT_p5_loop:
	s_waitcnt vmcnt(0)
	s_barrier
	ds_read_b64_tr_b16 v[66:67], v114 offset:0
	ds_read_b64_tr_b16 v[68:69], v115 offset:0
	ds_read_b64_tr_b16 v[70:71], v116 offset:0
	ds_read_b64_tr_b16 v[72:73], v117 offset:0
	ds_read_b128 v[74:77], v118 offset:16384
	ds_read_b128 v[78:81], v118 offset:20480
	ds_read_b64_tr_b16 v[82:83], v114 offset:4096
	ds_read_b64_tr_b16 v[84:85], v115 offset:4096
	ds_read_b64_tr_b16 v[86:87], v116 offset:4096
	ds_read_b64_tr_b16 v[88:89], v117 offset:4096
	ds_read_b128 v[90:93], v119 offset:16384
	ds_read_b128 v[94:97], v119 offset:20480
	s_add_u32 m0, s38, 0x8000
	s_nop 0
	global_load_lds_dwordx4 v[98:99], off
	v_lshl_add_u64 v[98:99], v[98:99], 0, s[28:29]
	s_add_u32 m0, s38, 0x8400
	s_nop 0
	global_load_lds_dwordx4 v[100:101], off
	v_lshl_add_u64 v[100:101], v[100:101], 0, s[28:29]
	s_waitcnt lgkmcnt(6)
	v_mfma_f32_32x32x16_bf16 v[50:65], v[66:69], v[74:77], v[50:65]
	v_mfma_f32_32x32x16_bf16 v[34:49], v[66:69], v[78:81], v[34:49]
	v_mfma_f32_32x32x16_bf16 v[18:33], v[70:73], v[74:77], v[18:33]
	v_mfma_f32_32x32x16_bf16 v[2:17], v[70:73], v[78:81], v[2:17]
	ds_read_b64_tr_b16 v[66:67], v114 offset:8192
	ds_read_b64_tr_b16 v[68:69], v115 offset:8192
	ds_read_b64_tr_b16 v[70:71], v116 offset:8192
	ds_read_b64_tr_b16 v[72:73], v117 offset:8192
	ds_read_b128 v[74:77], v120 offset:16384
	ds_read_b128 v[78:81], v120 offset:20480
	s_add_u32 m0, s38, 0x8800
	s_nop 0
	global_load_lds_dwordx4 v[102:103], off
	v_lshl_add_u64 v[102:103], v[102:103], 0, s[28:29]
	s_add_u32 m0, s38, 0x8c00
	s_nop 0
	global_load_lds_dwordx4 v[104:105], off
	v_lshl_add_u64 v[104:105], v[104:105], 0, s[28:29]
	s_waitcnt lgkmcnt(6)
	v_mfma_f32_32x32x16_bf16 v[50:65], v[82:85], v[90:93], v[50:65]
	v_mfma_f32_32x32x16_bf16 v[34:49], v[82:85], v[94:97], v[34:49]
	v_mfma_f32_32x32x16_bf16 v[18:33], v[86:89], v[90:93], v[18:33]
	v_mfma_f32_32x32x16_bf16 v[2:17], v[86:89], v[94:97], v[2:17]
	ds_read_b64_tr_b16 v[82:83], v114 offset:12288
	ds_read_b64_tr_b16 v[84:85], v115 offset:12288
	ds_read_b64_tr_b16 v[86:87], v116 offset:12288
	ds_read_b64_tr_b16 v[88:89], v117 offset:12288
	ds_read_b128 v[90:93], v121 offset:16384
	ds_read_b128 v[94:97], v121 offset:20480
	s_add_u32 m0, s38, 0xc010
	s_nop 0
	global_load_lds_dwordx4 v[106:107], off
	v_lshl_add_u64 v[106:107], v[106:107], 0, s[36:37]
	s_add_u32 m0, s38, 0xc410
	s_nop 0
	global_load_lds_dwordx4 v[108:109], off
	v_lshl_add_u64 v[108:109], v[108:109], 0, s[36:37]
	s_waitcnt lgkmcnt(6)
	v_mfma_f32_32x32x16_bf16 v[50:65], v[66:69], v[74:77], v[50:65]
	v_mfma_f32_32x32x16_bf16 v[34:49], v[66:69], v[78:81], v[34:49]
	v_mfma_f32_32x32x16_bf16 v[18:33], v[70:73], v[74:77], v[18:33]
	v_mfma_f32_32x32x16_bf16 v[2:17], v[70:73], v[78:81], v[2:17]
	s_add_u32 m0, s38, 0xc810
	s_nop 0
	global_load_lds_dwordx4 v[110:111], off
	v_lshl_add_u64 v[110:111], v[110:111], 0, s[36:37]
	s_add_u32 m0, s38, 0xcc10
	s_nop 0
	global_load_lds_dwordx4 v[112:113], off
	v_lshl_add_u64 v[112:113], v[112:113], 0, s[36:37]
	s_waitcnt lgkmcnt(0)
	v_mfma_f32_32x32x16_bf16 v[50:65], v[82:85], v[90:93], v[50:65]
	v_mfma_f32_32x32x16_bf16 v[34:49], v[82:85], v[94:97], v[34:49]
	v_mfma_f32_32x32x16_bf16 v[18:33], v[86:89], v[90:93], v[18:33]
	v_mfma_f32_32x32x16_bf16 v[2:17], v[86:89], v[94:97], v[2:17]
	s_waitcnt vmcnt(0)
	s_barrier
	ds_read_b64_tr_b16 v[66:67], v114 offset:32768
	ds_read_b64_tr_b16 v[68:69], v115 offset:32768
	ds_read_b64_tr_b16 v[70:71], v116 offset:32768
	ds_read_b64_tr_b16 v[72:73], v117 offset:32768
	ds_read_b128 v[74:77], v118 offset:49168
	ds_read_b128 v[78:81], v118 offset:53264
	ds_read_b64_tr_b16 v[82:83], v114 offset:36864
	ds_read_b64_tr_b16 v[84:85], v115 offset:36864
	ds_read_b64_tr_b16 v[86:87], v116 offset:36864
	ds_read_b64_tr_b16 v[88:89], v117 offset:36864
	ds_read_b128 v[90:93], v119 offset:49168
	ds_read_b128 v[94:97], v119 offset:53264
	s_add_u32 m0, s38, 0x0
	s_nop 0
	global_load_lds_dwordx4 v[98:99], off
	v_lshl_add_u64 v[98:99], v[98:99], 0, s[28:29]
	s_add_u32 m0, s38, 0x400
	s_nop 0
	global_load_lds_dwordx4 v[100:101], off
	v_lshl_add_u64 v[100:101], v[100:101], 0, s[28:29]
	s_waitcnt lgkmcnt(6)
	v_mfma_f32_32x32x16_bf16 v[50:65], v[66:69], v[74:77], v[50:65]
	v_mfma_f32_32x32x16_bf16 v[34:49], v[66:69], v[78:81], v[34:49]
	v_mfma_f32_32x32x16_bf16 v[18:33], v[70:73], v[74:77], v[18:33]
	v_mfma_f32_32x32x16_bf16 v[2:17], v[70:73], v[78:81], v[2:17]
	ds_read_b64_tr_b16 v[66:67], v114 offset:40960
	ds_read_b64_tr_b16 v[68:69], v115 offset:40960
	ds_read_b64_tr_b16 v[70:71], v116 offset:40960
	ds_read_b64_tr_b16 v[72:73], v117 offset:40960
	ds_read_b128 v[74:77], v120 offset:49168
	ds_read_b128 v[78:81], v120 offset:53264
	s_add_u32 m0, s38, 0x800
	s_nop 0
	global_load_lds_dwordx4 v[102:103], off
	v_lshl_add_u64 v[102:103], v[102:103], 0, s[28:29]
	s_add_u32 m0, s38, 0xc00
	s_nop 0
	global_load_lds_dwordx4 v[104:105], off
	v_lshl_add_u64 v[104:105], v[104:105], 0, s[28:29]
	s_waitcnt lgkmcnt(6)
	v_mfma_f32_32x32x16_bf16 v[50:65], v[82:85], v[90:93], v[50:65]
	v_mfma_f32_32x32x16_bf16 v[34:49], v[82:85], v[94:97], v[34:49]
	v_mfma_f32_32x32x16_bf16 v[18:33], v[86:89], v[90:93], v[18:33]
	v_mfma_f32_32x32x16_bf16 v[2:17], v[86:89], v[94:97], v[2:17]
	ds_read_b64_tr_b16 v[82:83], v114 offset:45056
	ds_read_b64_tr_b16 v[84:85], v115 offset:45056
	ds_read_b64_tr_b16 v[86:87], v116 offset:45056
	ds_read_b64_tr_b16 v[88:89], v117 offset:45056
	ds_read_b128 v[90:93], v121 offset:49168
	ds_read_b128 v[94:97], v121 offset:53264
	s_add_u32 m0, s38, 0x4000
	s_nop 0
	global_load_lds_dwordx4 v[106:107], off
	v_lshl_add_u64 v[106:107], v[106:107], 0, s[36:37]
	s_add_u32 m0, s38, 0x4400
	s_nop 0
	global_load_lds_dwordx4 v[108:109], off
	v_lshl_add_u64 v[108:109], v[108:109], 0, s[36:37]
	s_waitcnt lgkmcnt(6)
	v_mfma_f32_32x32x16_bf16 v[50:65], v[66:69], v[74:77], v[50:65]
	v_mfma_f32_32x32x16_bf16 v[34:49], v[66:69], v[78:81], v[34:49]
	v_mfma_f32_32x32x16_bf16 v[18:33], v[70:73], v[74:77], v[18:33]
	v_mfma_f32_32x32x16_bf16 v[2:17], v[70:73], v[78:81], v[2:17]
	s_add_u32 m0, s38, 0x4800
	s_nop 0
	global_load_lds_dwordx4 v[110:111], off
	v_lshl_add_u64 v[110:111], v[110:111], 0, s[36:37]
	s_add_u32 m0, s38, 0x4c00
	s_nop 0
	global_load_lds_dwordx4 v[112:113], off
	v_lshl_add_u64 v[112:113], v[112:113], 0, s[36:37]
	s_waitcnt lgkmcnt(0)
	v_mfma_f32_32x32x16_bf16 v[50:65], v[82:85], v[90:93], v[50:65]
	v_mfma_f32_32x32x16_bf16 v[34:49], v[82:85], v[94:97], v[34:49]
	v_mfma_f32_32x32x16_bf16 v[18:33], v[86:89], v[90:93], v[18:33]
	v_mfma_f32_32x32x16_bf16 v[2:17], v[86:89], v[94:97], v[2:17]
	s_sub_u32 s100, s100, 1
	s_cmp_lg_u32 s100, 0
	s_cbranch_scc1 .LgemmT_p5_loop
	s_waitcnt vmcnt(0)
	s_barrier
	ds_read_b64_tr_b16 v[66:67], v114 offset:0
	ds_read_b64_tr_b16 v[68:69], v115 offset:0
	ds_read_b64_tr_b16 v[70:71], v116 offset:0
	ds_read_b64_tr_b16 v[72:73], v117 offset:0
	ds_read_b128 v[74:77], v118 offset:16384
	ds_read_b128 v[78:81], v118 offset:20480
	ds_read_b64_tr_b16 v[82:83], v114 offset:4096
	ds_read_b64_tr_b16 v[84:85], v115 offset:4096
	ds_read_b64_tr_b16 v[86:87], v116 offset:4096
	ds_read_b64_tr_b16 v[88:89], v117 offset:4096
	ds_read_b128 v[90:93], v119 offset:16384
	ds_read_b128 v[94:97], v119 offset:20480
	s_add_u32 m0, s38, 0x8000
	s_nop 0
	global_load_lds_dwordx4 v[98:99], off
	v_lshl_add_u64 v[98:99], v[98:99], 0, s[28:29]
	s_add_u32 m0, s38, 0x8400
	s_nop 0
	global_load_lds_dwordx4 v[100:101], off
	v_lshl_add_u64 v[100:101], v[100:101], 0, s[28:29]
	s_waitcnt lgkmcnt(6)
	v_mfma_f32_32x32x16_bf16 v[50:65], v[66:69], v[74:77], v[50:65]
	v_mfma_f32_32x32x16_bf16 v[34:49], v[66:69], v[78:81], v[34:49]
	v_mfma_f32_32x32x16_bf16 v[18:33], v[70:73], v[74:77], v[18:33]
	v_mfma_f32_32x32x16_bf16 v[2:17], v[70:73], v[78:81], v[2:17]
	ds_read_b64_tr_b16 v[66:67], v114 offset:8192
	ds_read_b64_tr_b16 v[68:69], v115 offset:8192
	ds_read_b64_tr_b16 v[70:71], v116 offset:8192
	ds_read_b64_tr_b16 v[72:73], v117 offset:8192
	ds_read_b128 v[74:77], v120 offset:16384
	ds_read_b128 v[78:81], v120 offset:20480
	s_add_u32 m0, s38, 0x8800
	s_nop 0
	global_load_lds_dwordx4 v[102:103], off
	v_lshl_add_u64 v[102:103], v[102:103], 0, s[28:29]
	s_add_u32 m0, s38, 0x8c00
	s_nop 0
	global_load_lds_dwordx4 v[104:105], off
	v_lshl_add_u64 v[104:105], v[104:105], 0, s[28:29]
	s_waitcnt lgkmcnt(6)
	v_mfma_f32_32x32x16_bf16 v[50:65], v[82:85], v[90:93], v[50:65]
	v_mfma_f32_32x32x16_bf16 v[34:49], v[82:85], v[94:97], v[34:49]
	v_mfma_f32_32x32x16_bf16 v[18:33], v[86:89], v[90:93], v[18:33]
	v_mfma_f32_32x32x16_bf16 v[2:17], v[86:89], v[94:97], v[2:17]
	ds_read_b64_tr_b16 v[82:83], v114 offset:12288
	ds_read_b64_tr_b16 v[84:85], v115 offset:12288
	ds_read_b64_tr_b16 v[86:87], v116 offset:12288
	ds_read_b64_tr_b16 v[88:89], v117 offset:12288
	ds_read_b128 v[90:93], v121 offset:16384
	ds_read_b128 v[94:97], v121 offset:20480
	s_add_u32 m0, s38, 0xc010
	s_nop 0
	global_load_lds_dwordx4 v[106:107], off
	v_lshl_add_u64 v[106:107], v[106:107], 0, s[36:37]
	s_add_u32 m0, s38, 0xc410
	s_nop 0
	global_load_lds_dwordx4 v[108:109], off
	v_lshl_add_u64 v[108:109], v[108:109], 0, s[36:37]
	s_waitcnt lgkmcnt(6)
	v_mfma_f32_32x32x16_bf16 v[50:65], v[66:69], v[74:77], v[50:65]
	v_mfma_f32_32x32x16_bf16 v[34:49], v[66:69], v[78:81], v[34:49]
	v_mfma_f32_32x32x16_bf16 v[18:33], v[70:73], v[74:77], v[18:33]
	v_mfma_f32_32x32x16_bf16 v[2:17], v[70:73], v[78:81], v[2:17]
	s_add_u32 m0, s38, 0xc810
	s_nop 0
	global_load_lds_dwordx4 v[110:111], off
	v_lshl_add_u64 v[110:111], v[110:111], 0, s[36:37]
	s_add_u32 m0, s38, 0xcc10
	s_nop 0
	global_load_lds_dwordx4 v[112:113], off
	v_lshl_add_u64 v[112:113], v[112:113], 0, s[36:37]
	s_waitcnt lgkmcnt(0)
	v_mfma_f32_32x32x16_bf16 v[50:65], v[82:85], v[90:93], v[50:65]
	v_mfma_f32_32x32x16_bf16 v[34:49], v[82:85], v[94:97], v[34:49]
	v_mfma_f32_32x32x16_bf16 v[18:33], v[86:89], v[90:93], v[18:33]
	v_mfma_f32_32x32x16_bf16 v[2:17], v[86:89], v[94:97], v[2:17]
	s_waitcnt vmcnt(0)
	s_barrier
	ds_read_b64_tr_b16 v[66:67], v114 offset:32768
	ds_read_b64_tr_b16 v[68:69], v115 offset:32768
	ds_read_b64_tr_b16 v[70:71], v116 offset:32768
	ds_read_b64_tr_b16 v[72:73], v117 offset:32768
	ds_read_b128 v[74:77], v118 offset:49168
	ds_read_b128 v[78:81], v118 offset:53264
	ds_read_b64_tr_b16 v[82:83], v114 offset:36864
	ds_read_b64_tr_b16 v[84:85], v115 offset:36864
	ds_read_b64_tr_b16 v[86:87], v116 offset:36864
	ds_read_b64_tr_b16 v[88:89], v117 offset:36864
	ds_read_b128 v[90:93], v119 offset:49168
	ds_read_b128 v[94:97], v119 offset:53264
	s_waitcnt lgkmcnt(6)
	v_mfma_f32_32x32x16_bf16 v[50:65], v[66:69], v[74:77], v[50:65]
	v_mfma_f32_32x32x16_bf16 v[34:49], v[66:69], v[78:81], v[34:49]
	v_mfma_f32_32x32x16_bf16 v[18:33], v[70:73], v[74:77], v[18:33]
	v_mfma_f32_32x32x16_bf16 v[2:17], v[70:73], v[78:81], v[2:17]
	ds_read_b64_tr_b16 v[66:67], v114 offset:40960
	ds_read_b64_tr_b16 v[68:69], v115 offset:40960
	ds_read_b64_tr_b16 v[70:71], v116 offset:40960
	ds_read_b64_tr_b16 v[72:73], v117 offset:40960
	ds_read_b128 v[74:77], v120 offset:49168
	ds_read_b128 v[78:81], v120 offset:53264
	s_waitcnt lgkmcnt(6)
	v_mfma_f32_32x32x16_bf16 v[50:65], v[82:85], v[90:93], v[50:65]
	v_mfma_f32_32x32x16_bf16 v[34:49], v[82:85], v[94:97], v[34:49]
	v_mfma_f32_32x32x16_bf16 v[18:33], v[86:89], v[90:93], v[18:33]
	v_mfma_f32_32x32x16_bf16 v[2:17], v[86:89], v[94:97], v[2:17]
	ds_read_b64_tr_b16 v[82:83], v114 offset:45056
	ds_read_b64_tr_b16 v[84:85], v115 offset:45056
	ds_read_b64_tr_b16 v[86:87], v116 offset:45056
	ds_read_b64_tr_b16 v[88:89], v117 offset:45056
	ds_read_b128 v[90:93], v121 offset:49168
	ds_read_b128 v[94:97], v121 offset:53264
	s_waitcnt lgkmcnt(6)
	v_mfma_f32_32x32x16_bf16 v[50:65], v[66:69], v[74:77], v[50:65]
	v_mfma_f32_32x32x16_bf16 v[34:49], v[66:69], v[78:81], v[34:49]
	v_mfma_f32_32x32x16_bf16 v[18:33], v[70:73], v[74:77], v[18:33]
	v_mfma_f32_32x32x16_bf16 v[2:17], v[70:73], v[78:81], v[2:17]
	s_waitcnt lgkmcnt(0)
	v_mfma_f32_32x32x16_bf16 v[50:65], v[82:85], v[90:93], v[50:65]
	v_mfma_f32_32x32x16_bf16 v[34:49], v[82:85], v[94:97], v[34:49]
	v_mfma_f32_32x32x16_bf16 v[18:33], v[86:89], v[90:93], v[18:33]
	v_mfma_f32_32x32x16_bf16 v[2:17], v[86:89], v[94:97], v[2:17]
	v_readlane_b32 s38, v248, 2
	v_readlane_b32 s39, v248, 3
	s_nop 3
	v_mov_b32_e32 v66, v184
	v_readlane_b32 s36, v248, 6
	v_readlane_b32 s37, v248, 7
	v_readlane_b32 s28, v248, 8
	v_readlane_b32 s29, v248, 9
	v_readlane_b32 s0, v245, 5
	v_readlane_b32 s1, v245, 6
	v_ashrrev_i32_e32 v1, 1, v66
	v_and_b32_e32 v1, 0xffffffc0, v1
	v_lshrrev_b32_e32 v67, 3, v66
	v_and_b32_e32 v67, 4, v67
	v_add_u32_e32 v1, s24, v1
	v_or_b32_e32 v1, v1, v67
	v_and_b32_e32 v68, 0x5f, v66
	v_or_b32_e32 v68, s23, v68
	v_lshlrev_b32_e32 v69, 2, v68
	v_lshl_add_u32 v70, v1, 12, v69
	s_sub_u32 s28, s28, 0x2000000
	s_subb_u32 s29, s29, 0
	s_cmp_gt_i32 s22, 63
	s_cselect_b32 s36, s28, s36
	s_cselect_b32 s37, s29, s37
	s_add_i32 s28, s24, 0xffffe000
	s_ashr_i32 s28, s28, 12
	s_mulk_i32 s28, 0xc00
	s_addk_i32 s28, 0x800
	s_cmp_gt_i32 s22, 63
	s_cselect_b32 s28, s28, 0x6800
	v_add_lshl_u32 v71, v68, s28, 2
	v_mov_b32_e32 v74, v70
	v_add_u32_e32 v75, 0x1000, v70
	v_add_u32_e32 v76, 0x2000, v70
	v_add_u32_e32 v77, 0x3000, v70
	v_add_u32_e32 v78, 0x8000, v70
	v_add_u32_e32 v79, 0x9000, v70
	v_add_u32_e32 v80, 0xa000, v70
	v_add_u32_e32 v81, 0xb000, v70
	v_add_u32_e32 v82, 0x10000, v70
	v_add_u32_e32 v83, 0x11000, v70
	v_add_u32_e32 v84, 0x12000, v70
	v_add_u32_e32 v85, 0x13000, v70
	v_add_u32_e32 v86, 0x18000, v70
	v_add_u32_e32 v87, 0x19000, v70
	v_add_u32_e32 v88, 0x1a000, v70
	v_add_u32_e32 v89, 0x1b000, v70
	global_load_dword v122, v71, s[0:1]
	global_load_dword v123, v71, s[0:1] offset:128
	global_load_dword v90, v74, s[36:37] nt
	global_load_dword v91, v75, s[36:37] nt
	global_load_dword v92, v76, s[36:37] nt
	global_load_dword v93, v77, s[36:37] nt
	global_load_dword v94, v78, s[36:37] nt
	global_load_dword v95, v79, s[36:37] nt
	global_load_dword v96, v80, s[36:37] nt
	global_load_dword v97, v81, s[36:37] nt
	global_load_dword v98, v82, s[36:37] nt
	global_load_dword v99, v83, s[36:37] nt
	global_load_dword v100, v84, s[36:37] nt
	global_load_dword v101, v85, s[36:37] nt
	global_load_dword v102, v86, s[36:37] nt
	global_load_dword v103, v87, s[36:37] nt
	global_load_dword v104, v88, s[36:37] nt
	global_load_dword v105, v89, s[36:37] nt
	global_load_dword v106, v74, s[36:37] offset:128 nt
	global_load_dword v107, v75, s[36:37] offset:128 nt
	global_load_dword v108, v76, s[36:37] offset:128 nt
	global_load_dword v109, v77, s[36:37] offset:128 nt
	global_load_dword v110, v78, s[36:37] offset:128 nt
	global_load_dword v111, v79, s[36:37] offset:128 nt
	global_load_dword v112, v80, s[36:37] offset:128 nt
	global_load_dword v113, v81, s[36:37] offset:128 nt
	global_load_dword v114, v82, s[36:37] offset:128 nt
	global_load_dword v115, v83, s[36:37] offset:128 nt
	global_load_dword v116, v84, s[36:37] offset:128 nt
	global_load_dword v117, v85, s[36:37] offset:128 nt
	global_load_dword v118, v86, s[36:37] offset:128 nt
	global_load_dword v119, v87, s[36:37] offset:128 nt
	global_load_dword v120, v88, s[36:37] offset:128 nt
	global_load_dword v121, v89, s[36:37] offset:128 nt
	s_waitcnt vmcnt(31)
	v_fmac_f32_e32 v90, v50, v122
	global_store_dword v74, v90, s[38:39]
	s_waitcnt vmcnt(31)
	v_fmac_f32_e32 v91, v51, v122
	global_store_dword v75, v91, s[38:39]
	s_waitcnt vmcnt(31)
	v_fmac_f32_e32 v92, v52, v122
	global_store_dword v76, v92, s[38:39]
	s_waitcnt vmcnt(31)
	v_fmac_f32_e32 v93, v53, v122
	global_store_dword v77, v93, s[38:39]
	s_waitcnt vmcnt(31)
	v_fmac_f32_e32 v94, v54, v122
	global_store_dword v78, v94, s[38:39]
	s_waitcnt vmcnt(31)
	v_fmac_f32_e32 v95, v55, v122
	global_store_dword v79, v95, s[38:39]
	s_waitcnt vmcnt(31)
	v_fmac_f32_e32 v96, v56, v122
	global_store_dword v80, v96, s[38:39]
	s_waitcnt vmcnt(31)
	v_fmac_f32_e32 v97, v57, v122
	global_store_dword v81, v97, s[38:39]
	s_waitcnt vmcnt(31)
	v_fmac_f32_e32 v98, v58, v122
	global_store_dword v82, v98, s[38:39]
	s_waitcnt vmcnt(31)
	v_fmac_f32_e32 v99, v59, v122
	global_store_dword v83, v99, s[38:39]
	s_waitcnt vmcnt(31)
	v_fmac_f32_e32 v100, v60, v122
	global_store_dword v84, v100, s[38:39]
	s_waitcnt vmcnt(31)
	v_fmac_f32_e32 v101, v61, v122
	global_store_dword v85, v101, s[38:39]
	s_waitcnt vmcnt(31)
	v_fmac_f32_e32 v102, v62, v122
	global_store_dword v86, v102, s[38:39]
	s_waitcnt vmcnt(31)
	v_fmac_f32_e32 v103, v63, v122
	global_store_dword v87, v103, s[38:39]
	s_waitcnt vmcnt(31)
	v_fmac_f32_e32 v104, v64, v122
	global_store_dword v88, v104, s[38:39]
	s_waitcnt vmcnt(31)
	v_fmac_f32_e32 v105, v65, v122
	global_store_dword v89, v105, s[38:39]
	v_add_u32_e32 v50, 0x20000, v74
	v_add_u32_e32 v51, 0x20000, v75
	v_add_u32_e32 v52, 0x20000, v76
	v_add_u32_e32 v53, 0x20000, v77
	v_add_u32_e32 v54, 0x20000, v78
	v_add_u32_e32 v55, 0x20000, v79
	v_add_u32_e32 v56, 0x20000, v80
	v_add_u32_e32 v57, 0x20000, v81
	v_add_u32_e32 v58, 0x20000, v82
	v_add_u32_e32 v59, 0x20000, v83
	v_add_u32_e32 v60, 0x20000, v84
	v_add_u32_e32 v61, 0x20000, v85
	v_add_u32_e32 v62, 0x20000, v86
	v_add_u32_e32 v63, 0x20000, v87
	v_add_u32_e32 v64, 0x20000, v88
	v_add_u32_e32 v65, 0x20000, v89
	global_load_dword v90, v50, s[36:37] nt
	global_load_dword v91, v51, s[36:37] nt
	global_load_dword v92, v52, s[36:37] nt
	global_load_dword v93, v53, s[36:37] nt
	global_load_dword v94, v54, s[36:37] nt
	global_load_dword v95, v55, s[36:37] nt
	global_load_dword v96, v56, s[36:37] nt
	global_load_dword v97, v57, s[36:37] nt
	global_load_dword v98, v58, s[36:37] nt
	global_load_dword v99, v59, s[36:37] nt
	global_load_dword v100, v60, s[36:37] nt
	global_load_dword v101, v61, s[36:37] nt
	global_load_dword v102, v62, s[36:37] nt
	global_load_dword v103, v63, s[36:37] nt
	global_load_dword v104, v64, s[36:37] nt
	global_load_dword v105, v65, s[36:37] nt
	s_waitcnt vmcnt(47)
	v_fmac_f32_e32 v106, v34, v123
	global_store_dword v74, v106, s[38:39] offset:128
	s_waitcnt vmcnt(47)
	v_fmac_f32_e32 v107, v35, v123
	global_store_dword v75, v107, s[38:39] offset:128
	s_waitcnt vmcnt(47)
	v_fmac_f32_e32 v108, v36, v123
	global_store_dword v76, v108, s[38:39] offset:128
	s_waitcnt vmcnt(47)
	v_fmac_f32_e32 v109, v37, v123
	global_store_dword v77, v109, s[38:39] offset:128
	s_waitcnt vmcnt(47)
	v_fmac_f32_e32 v110, v38, v123
	global_store_dword v78, v110, s[38:39] offset:128
	s_waitcnt vmcnt(47)
	v_fmac_f32_e32 v111, v39, v123
	global_store_dword v79, v111, s[38:39] offset:128
	s_waitcnt vmcnt(47)
	v_fmac_f32_e32 v112, v40, v123
	global_store_dword v80, v112, s[38:39] offset:128
	s_waitcnt vmcnt(47)
	v_fmac_f32_e32 v113, v41, v123
	global_store_dword v81, v113, s[38:39] offset:128
	s_waitcnt vmcnt(47)
	v_fmac_f32_e32 v114, v42, v123
	global_store_dword v82, v114, s[38:39] offset:128
	s_waitcnt vmcnt(47)
	v_fmac_f32_e32 v115, v43, v123
	global_store_dword v83, v115, s[38:39] offset:128
	s_waitcnt vmcnt(47)
	v_fmac_f32_e32 v116, v44, v123
	global_store_dword v84, v116, s[38:39] offset:128
	s_waitcnt vmcnt(47)
	v_fmac_f32_e32 v117, v45, v123
	global_store_dword v85, v117, s[38:39] offset:128
	s_waitcnt vmcnt(47)
	v_fmac_f32_e32 v118, v46, v123
	global_store_dword v86, v118, s[38:39] offset:128
	s_waitcnt vmcnt(47)
	v_fmac_f32_e32 v119, v47, v123
	global_store_dword v87, v119, s[38:39] offset:128
	s_waitcnt vmcnt(47)
	v_fmac_f32_e32 v120, v48, v123
	global_store_dword v88, v120, s[38:39] offset:128
	s_waitcnt vmcnt(47)
	v_fmac_f32_e32 v121, v49, v123
	global_store_dword v89, v121, s[38:39] offset:128
	global_load_dword v106, v50, s[36:37] offset:128 nt
	global_load_dword v107, v51, s[36:37] offset:128 nt
	global_load_dword v108, v52, s[36:37] offset:128 nt
	global_load_dword v109, v53, s[36:37] offset:128 nt
	global_load_dword v110, v54, s[36:37] offset:128 nt
	global_load_dword v111, v55, s[36:37] offset:128 nt
	global_load_dword v112, v56, s[36:37] offset:128 nt
	global_load_dword v113, v57, s[36:37] offset:128 nt
	global_load_dword v114, v58, s[36:37] offset:128 nt
	global_load_dword v115, v59, s[36:37] offset:128 nt
	global_load_dword v116, v60, s[36:37] offset:128 nt
	global_load_dword v117, v61, s[36:37] offset:128 nt
	global_load_dword v118, v62, s[36:37] offset:128 nt
	global_load_dword v119, v63, s[36:37] offset:128 nt
	global_load_dword v120, v64, s[36:37] offset:128 nt
	global_load_dword v121, v65, s[36:37] offset:128 nt
	s_waitcnt vmcnt(47)
	v_fmac_f32_e32 v90, v18, v122
	global_store_dword v50, v90, s[38:39]
	s_waitcnt vmcnt(47)
	v_fmac_f32_e32 v91, v19, v122
	global_store_dword v51, v91, s[38:39]
	s_waitcnt vmcnt(47)
	v_fmac_f32_e32 v92, v20, v122
	global_store_dword v52, v92, s[38:39]
	s_waitcnt vmcnt(47)
	v_fmac_f32_e32 v93, v21, v122
	global_store_dword v53, v93, s[38:39]
	s_waitcnt vmcnt(47)
	v_fmac_f32_e32 v94, v22, v122
	global_store_dword v54, v94, s[38:39]
	s_waitcnt vmcnt(47)
	v_fmac_f32_e32 v95, v23, v122
	global_store_dword v55, v95, s[38:39]
	s_waitcnt vmcnt(47)
	v_fmac_f32_e32 v96, v24, v122
	global_store_dword v56, v96, s[38:39]
	s_waitcnt vmcnt(47)
	v_fmac_f32_e32 v97, v25, v122
	global_store_dword v57, v97, s[38:39]
	s_waitcnt vmcnt(47)
	v_fmac_f32_e32 v98, v26, v122
	global_store_dword v58, v98, s[38:39]
	s_waitcnt vmcnt(47)
	v_fmac_f32_e32 v99, v27, v122
	global_store_dword v59, v99, s[38:39]
	s_waitcnt vmcnt(47)
	v_fmac_f32_e32 v100, v28, v122
	global_store_dword v60, v100, s[38:39]
	s_waitcnt vmcnt(47)
	v_fmac_f32_e32 v101, v29, v122
	global_store_dword v61, v101, s[38:39]
	s_waitcnt vmcnt(47)
	v_fmac_f32_e32 v102, v30, v122
	global_store_dword v62, v102, s[38:39]
	s_waitcnt vmcnt(47)
	v_fmac_f32_e32 v103, v31, v122
	global_store_dword v63, v103, s[38:39]
	s_waitcnt vmcnt(47)
	v_fmac_f32_e32 v104, v32, v122
	global_store_dword v64, v104, s[38:39]
	s_waitcnt vmcnt(47)
	v_fmac_f32_e32 v105, v33, v122
	global_store_dword v65, v105, s[38:39]
	s_waitcnt vmcnt(31)
	v_fmac_f32_e32 v106, v2, v123
	global_store_dword v50, v106, s[38:39] offset:128
	s_waitcnt vmcnt(31)
	v_fmac_f32_e32 v107, v3, v123
	global_store_dword v51, v107, s[38:39] offset:128
	s_waitcnt vmcnt(31)
	v_fmac_f32_e32 v108, v4, v123
	global_store_dword v52, v108, s[38:39] offset:128
	s_waitcnt vmcnt(31)
	v_fmac_f32_e32 v109, v5, v123
	global_store_dword v53, v109, s[38:39] offset:128
	s_waitcnt vmcnt(31)
	v_fmac_f32_e32 v110, v6, v123
	global_store_dword v54, v110, s[38:39] offset:128
	s_waitcnt vmcnt(31)
	v_fmac_f32_e32 v111, v7, v123
	global_store_dword v55, v111, s[38:39] offset:128
	s_waitcnt vmcnt(31)
	v_fmac_f32_e32 v112, v8, v123
	global_store_dword v56, v112, s[38:39] offset:128
	s_waitcnt vmcnt(31)
	v_fmac_f32_e32 v113, v9, v123
	global_store_dword v57, v113, s[38:39] offset:128
	s_waitcnt vmcnt(31)
	v_fmac_f32_e32 v114, v10, v123
	global_store_dword v58, v114, s[38:39] offset:128
	s_waitcnt vmcnt(31)
	v_fmac_f32_e32 v115, v11, v123
	global_store_dword v59, v115, s[38:39] offset:128
	s_waitcnt vmcnt(31)
	v_fmac_f32_e32 v116, v12, v123
	global_store_dword v60, v116, s[38:39] offset:128
	s_waitcnt vmcnt(31)
	v_fmac_f32_e32 v117, v13, v123
	global_store_dword v61, v117, s[38:39] offset:128
	s_waitcnt vmcnt(31)
	v_fmac_f32_e32 v118, v14, v123
	global_store_dword v62, v118, s[38:39] offset:128
	s_waitcnt vmcnt(31)
	v_fmac_f32_e32 v119, v15, v123
	global_store_dword v63, v119, s[38:39] offset:128
	s_waitcnt vmcnt(31)
	v_fmac_f32_e32 v120, v16, v123
	global_store_dword v64, v120, s[38:39] offset:128
	s_waitcnt vmcnt(31)
	v_fmac_f32_e32 v121, v17, v123
	global_store_dword v65, v121, s[38:39] offset:128
	v_readlane_b32 s0, v246, 1
	s_nop 1
	s_add_i32 s2, s2, s0
	s_cmpk_gt_i32 s2, 0x13f
	s_cbranch_scc0 .LBB0_599
	v_readlane_b32 s52, v245, 56
	v_readlane_b32 s54, v245, 58
	v_readlane_b32 s55, v245, 59
	v_readlane_b32 s56, v245, 60
	v_readlane_b32 s57, v245, 61
	v_readlane_b32 s58, v245, 62
	v_readlane_b32 s59, v245, 63
	v_readlane_b32 s60, v244, 0
	v_readlane_b32 s61, v244, 1
	v_readlane_b32 s62, v244, 2
	v_readlane_b32 s63, v244, 3
	v_readlane_b32 s64, v244, 4
	v_readlane_b32 s65, v244, 5
	v_readlane_b32 s66, v244, 6
	v_readlane_b32 s67, v244, 7
	s_movk_i32 s43, 0x1fff
	v_readlane_b32 s53, v245, 57
